# P4 epilogue hand-written; final rmsnorm (P5) folded in via 8-workgroup row-block rendezvous; grid barrier 5 + P5 removed; output from f32 h2 (no bf16 H2B round trip)
# speedup vs baseline: 1.0326x; 1.0246x over previous
.LBB0_769:
	s_or_b64 exec, exec, s[4:5]
	v_mov_b32_e32 v8, v225
	s_waitcnt lgkmcnt(0)
	s_barrier
	s_mov_b32 s99, 0
	s_and_b32 s87, s2, 7
	s_lshl_b32 s87, s87, 2
	s_bfe_u32 s86, s2, 0x20003
	s_add_i32 s87, s87, s86
	s_lshl_b32 s87, s87, 6
	s_add_u32 s88, s22, s87
	s_addc_u32 s89, s23, 0
	s_add_u32 s88, s88, 0x83800
	s_addc_u32 s89, s89, 0
	s_and_b64 vcc, exec, s[8:9]
	v_readfirstlane_b32 s6, v8
	s_cbranch_vccnz .LBB0_775
	s_ashr_i32 s3, s2, 31
	s_lshr_b32 s3, s3, 29
	s_add_i32 s16, s2, s3
	s_and_b32 s3, s16, -8
	s_sub_i32 s3, s2, s3
	s_cmp_gt_i32 s3, -1
	s_cbranch_scc0 .LBB0_772
	s_lshl_b32 s7, s3, 6
	s_ashr_i32 s4, s16, 3
	s_cbranch_execz .LBB0_773
	s_branch .LBB0_774

.LBB0_791:
	v_lshl_add_u32 v146, s44, 8, v154
	v_lshl_or_b32 v144, s46, 8, v156
	v_xor_b32_e32 v149, 16, v161
	v_xor_b32_e32 v150, 32, v161
	v_lshl_add_u32 v145, v146, 11, v144
	v_lshlrev_b32_e32 v149, 2, v149
	v_lshlrev_b32_e32 v150, 2, v150
	v_lshlrev_b32_e32 v148, 2, v146
	v_lshlrev_b32_e32 v147, 1, v145
	s_mov_b64 s[48:49], s[12:13]
	s_mov_b64 s[50:51], s[14:15]
	global_load_dword v176, v148, s[22:23] offset:0
	global_load_dwordx4 v[184:187], v147, s[48:49] offset:0
	global_load_dwordx4 v[188:191], v147, s[50:51] offset:0
	global_load_dwordx4 v[192:195], v147, s[48:49] offset:256
	global_load_dwordx4 v[196:199], v147, s[50:51] offset:256
	s_add_u32 s48, s12, 0x10000
	s_addc_u32 s49, s13, 0
	s_add_u32 s50, s14, 0x10000
	s_addc_u32 s51, s15, 0
	global_load_dword v177, v148, s[22:23] offset:64
	global_load_dwordx4 v[200:203], v147, s[48:49] offset:0
	global_load_dwordx4 v[204:207], v147, s[50:51] offset:0
	global_load_dwordx4 v[208:211], v147, s[48:49] offset:256
	global_load_dwordx4 v[212:215], v147, s[50:51] offset:256
	s_add_u32 s48, s12, 0x20000
	s_addc_u32 s49, s13, 0
	s_add_u32 s50, s14, 0x20000
	s_addc_u32 s51, s15, 0
	global_load_dword v178, v148, s[22:23] offset:128
	global_load_dwordx4 v[216:219], v147, s[48:49] offset:0
	global_load_dwordx4 v[220:223], v147, s[50:51] offset:0
	global_load_dwordx4 v[226:229], v147, s[48:49] offset:256
	global_load_dwordx4 v[230:233], v147, s[50:51] offset:256
	s_add_u32 s48, s12, 0x30000
	s_addc_u32 s49, s13, 0
	s_add_u32 s50, s14, 0x30000
	s_addc_u32 s51, s15, 0
	global_load_dword v179, v148, s[22:23] offset:192
	global_load_dwordx4 v[234:237], v147, s[48:49] offset:0
	global_load_dwordx4 v[238:241], v147, s[50:51] offset:0
	global_load_dwordx4 v[242:245], v147, s[48:49] offset:256
	global_load_dwordx4 v[246:249], v147, s[50:51] offset:256
	s_waitcnt vmcnt(15)
	v_fmamk_f32 v151, v176, 0x3a000000, v160
	v_mul_f32_e32 v152, 0x4b800000, v151
	v_cmp_gt_f32_e32 vcc, s65, v151
	s_nop 1
	v_cndmask_b32_e32 v151, v151, v152, vcc
	v_rsq_f32_e32 v151, v151
	s_nop 0
	v_mul_f32_e32 v152, 0x45800000, v151
	v_cndmask_b32_e32 v151, v151, v152, vcc
	v_lshlrev_b32_e32 v162, 16, v184
	v_and_b32_e32 v163, 0xffff0000, v184
	v_lshlrev_b32_e32 v170, 16, v188
	v_and_b32_e32 v171, 0xffff0000, v188
	v_lshlrev_b32_e32 v164, 16, v185
	v_and_b32_e32 v165, 0xffff0000, v185
	v_lshlrev_b32_e32 v172, 16, v189
	v_and_b32_e32 v173, 0xffff0000, v189
	v_lshlrev_b32_e32 v166, 16, v186
	v_and_b32_e32 v167, 0xffff0000, v186
	v_lshlrev_b32_e32 v174, 16, v190
	v_and_b32_e32 v175, 0xffff0000, v190
	v_lshlrev_b32_e32 v168, 16, v187
	v_and_b32_e32 v169, 0xffff0000, v187
	v_lshlrev_b32_e32 v180, 16, v191
	v_and_b32_e32 v181, 0xffff0000, v191
	v_mul_f32_e32 v124, v124, v151
	v_mul_f32_e32 v125, v125, v151
	v_mul_f32_e32 v126, v126, v151
	v_mul_f32_e32 v127, v127, v151
	v_mul_f32_e32 v120, v120, v151
	v_mul_f32_e32 v121, v121, v151
	v_mul_f32_e32 v122, v122, v151
	v_mul_f32_e32 v123, v123, v151
	v_mul_f32_e32 v124, 0xbfb8aa3b, v124
	v_mul_f32_e32 v125, 0xbfb8aa3b, v125
	v_mul_f32_e32 v126, 0xbfb8aa3b, v126
	v_mul_f32_e32 v127, 0xbfb8aa3b, v127
	v_mul_f32_e32 v120, 0xbfb8aa3b, v120
	v_mul_f32_e32 v121, 0xbfb8aa3b, v121
	v_mul_f32_e32 v122, 0xbfb8aa3b, v122
	v_mul_f32_e32 v123, 0xbfb8aa3b, v123
	v_exp_f32_e32 v124, v124
	v_exp_f32_e32 v125, v125
	v_exp_f32_e32 v126, v126
	v_exp_f32_e32 v127, v127
	v_exp_f32_e32 v120, v120
	v_exp_f32_e32 v121, v121
	v_exp_f32_e32 v122, v122
	v_exp_f32_e32 v123, v123
	v_add_f32_e32 v124, 1.0, v124
	v_add_f32_e32 v125, 1.0, v125
	v_add_f32_e32 v126, 1.0, v126
	v_add_f32_e32 v127, 1.0, v127
	v_add_f32_e32 v120, 1.0, v120
	v_add_f32_e32 v121, 1.0, v121
	v_add_f32_e32 v122, 1.0, v122
	v_add_f32_e32 v123, 1.0, v123
	v_rcp_f32_e32 v124, v124
	v_rcp_f32_e32 v125, v125
	v_rcp_f32_e32 v126, v126
	v_rcp_f32_e32 v127, v127
	v_rcp_f32_e32 v120, v120
	v_rcp_f32_e32 v121, v121
	v_rcp_f32_e32 v122, v122
	v_rcp_f32_e32 v123, v123
	v_fma_f32 v124, v124, v170, v162
	v_fma_f32 v125, v125, v171, v163
	v_fma_f32 v126, v126, v172, v164
	v_fma_f32 v127, v127, v173, v165
	v_fma_f32 v120, v120, v174, v166
	v_fma_f32 v121, v121, v175, v167
	v_fma_f32 v122, v122, v180, v168
	v_fma_f32 v123, v123, v181, v169
	v_mul_f32_e32 v152, v125, v125
	v_mul_f32_e32 v153, v127, v127
	v_mul_f32_e32 v182, v121, v121
	v_mul_f32_e32 v183, v123, v123
	v_fmac_f32_e32 v152, v124, v124
	v_fmac_f32_e32 v153, v126, v126
	v_fmac_f32_e32 v182, v120, v120
	v_fmac_f32_e32 v183, v122, v122
	v_add_f32_e32 v152, v152, v153
	v_add_f32_e32 v182, v182, v183
	v_add_f32_e32 v224, v152, v182
	v_lshlrev_b32_e32 v162, 16, v192
	v_and_b32_e32 v163, 0xffff0000, v192
	v_lshlrev_b32_e32 v170, 16, v196
	v_and_b32_e32 v171, 0xffff0000, v196
	v_lshlrev_b32_e32 v164, 16, v193
	v_and_b32_e32 v165, 0xffff0000, v193
	v_lshlrev_b32_e32 v172, 16, v197
	v_and_b32_e32 v173, 0xffff0000, v197
	v_lshlrev_b32_e32 v166, 16, v194
	v_and_b32_e32 v167, 0xffff0000, v194
	v_lshlrev_b32_e32 v174, 16, v198
	v_and_b32_e32 v175, 0xffff0000, v198
	v_lshlrev_b32_e32 v168, 16, v195
	v_and_b32_e32 v169, 0xffff0000, v195
	v_lshlrev_b32_e32 v180, 16, v199
	v_and_b32_e32 v181, 0xffff0000, v199
	v_mul_f32_e32 v116, v116, v151
	v_mul_f32_e32 v117, v117, v151
	v_mul_f32_e32 v118, v118, v151
	v_mul_f32_e32 v119, v119, v151
	v_mul_f32_e32 v112, v112, v151
	v_mul_f32_e32 v113, v113, v151
	v_mul_f32_e32 v114, v114, v151
	v_mul_f32_e32 v115, v115, v151
	v_mul_f32_e32 v116, 0xbfb8aa3b, v116
	v_mul_f32_e32 v117, 0xbfb8aa3b, v117
	v_mul_f32_e32 v118, 0xbfb8aa3b, v118
	v_mul_f32_e32 v119, 0xbfb8aa3b, v119
	v_mul_f32_e32 v112, 0xbfb8aa3b, v112
	v_mul_f32_e32 v113, 0xbfb8aa3b, v113
	v_mul_f32_e32 v114, 0xbfb8aa3b, v114
	v_mul_f32_e32 v115, 0xbfb8aa3b, v115
	v_exp_f32_e32 v116, v116
	v_exp_f32_e32 v117, v117
	v_exp_f32_e32 v118, v118
	v_exp_f32_e32 v119, v119
	v_exp_f32_e32 v112, v112
	v_exp_f32_e32 v113, v113
	v_exp_f32_e32 v114, v114
	v_exp_f32_e32 v115, v115
	v_add_f32_e32 v116, 1.0, v116
	v_add_f32_e32 v117, 1.0, v117
	v_add_f32_e32 v118, 1.0, v118
	v_add_f32_e32 v119, 1.0, v119
	v_add_f32_e32 v112, 1.0, v112
	v_add_f32_e32 v113, 1.0, v113
	v_add_f32_e32 v114, 1.0, v114
	v_add_f32_e32 v115, 1.0, v115
	v_rcp_f32_e32 v116, v116
	v_rcp_f32_e32 v117, v117
	v_rcp_f32_e32 v118, v118
	v_rcp_f32_e32 v119, v119
	v_rcp_f32_e32 v112, v112
	v_rcp_f32_e32 v113, v113
	v_rcp_f32_e32 v114, v114
	v_rcp_f32_e32 v115, v115
	v_fma_f32 v116, v116, v170, v162
	v_fma_f32 v117, v117, v171, v163
	v_fma_f32 v118, v118, v172, v164
	v_fma_f32 v119, v119, v173, v165
	v_fma_f32 v112, v112, v174, v166
	v_fma_f32 v113, v113, v175, v167
	v_fma_f32 v114, v114, v180, v168
	v_fma_f32 v115, v115, v181, v169
	v_mul_f32_e32 v152, v117, v117
	v_mul_f32_e32 v153, v119, v119
	v_mul_f32_e32 v182, v113, v113
	v_mul_f32_e32 v183, v115, v115
	v_fmac_f32_e32 v152, v116, v116
	v_fmac_f32_e32 v153, v118, v118
	v_fmac_f32_e32 v182, v112, v112
	v_fmac_f32_e32 v183, v114, v114
	v_add_f32_e32 v152, v152, v153
	v_add_f32_e32 v182, v182, v183
	v_add_f32_e32 v250, v152, v182
	s_add_u32 s48, s12, 0x80000
	s_addc_u32 s49, s13, 0
	s_add_u32 s50, s14, 0x80000
	s_addc_u32 s51, s15, 0
	global_load_dword v176, v148, s[22:23] offset:512
	global_load_dwordx4 v[184:187], v147, s[48:49] offset:0
	global_load_dwordx4 v[188:191], v147, s[50:51] offset:0
	global_load_dwordx4 v[192:195], v147, s[48:49] offset:256
	global_load_dwordx4 v[196:199], v147, s[50:51] offset:256
	v_add_f32_e32 v251, v224, v250
	ds_bpermute_b32 v252, v149, v251
	s_waitcnt vmcnt(15)
	v_fmamk_f32 v151, v177, 0x3a000000, v160
	v_mul_f32_e32 v152, 0x4b800000, v151
	v_cmp_gt_f32_e32 vcc, s65, v151
	s_nop 1
	v_cndmask_b32_e32 v151, v151, v152, vcc
	v_rsq_f32_e32 v151, v151
	s_nop 0
	v_mul_f32_e32 v152, 0x45800000, v151
	v_cndmask_b32_e32 v151, v151, v152, vcc
	v_lshlrev_b32_e32 v162, 16, v200
	v_and_b32_e32 v163, 0xffff0000, v200
	v_lshlrev_b32_e32 v170, 16, v204
	v_and_b32_e32 v171, 0xffff0000, v204
	v_lshlrev_b32_e32 v164, 16, v201
	v_and_b32_e32 v165, 0xffff0000, v201
	v_lshlrev_b32_e32 v172, 16, v205
	v_and_b32_e32 v173, 0xffff0000, v205
	v_lshlrev_b32_e32 v166, 16, v202
	v_and_b32_e32 v167, 0xffff0000, v202
	v_lshlrev_b32_e32 v174, 16, v206
	v_and_b32_e32 v175, 0xffff0000, v206
	v_lshlrev_b32_e32 v168, 16, v203
	v_and_b32_e32 v169, 0xffff0000, v203
	v_lshlrev_b32_e32 v180, 16, v207
	v_and_b32_e32 v181, 0xffff0000, v207
	v_mul_f32_e32 v108, v108, v151
	v_mul_f32_e32 v109, v109, v151
	v_mul_f32_e32 v110, v110, v151
	v_mul_f32_e32 v111, v111, v151
	v_mul_f32_e32 v104, v104, v151
	v_mul_f32_e32 v105, v105, v151
	v_mul_f32_e32 v106, v106, v151
	v_mul_f32_e32 v107, v107, v151
	v_mul_f32_e32 v108, 0xbfb8aa3b, v108
	v_mul_f32_e32 v109, 0xbfb8aa3b, v109
	v_mul_f32_e32 v110, 0xbfb8aa3b, v110
	v_mul_f32_e32 v111, 0xbfb8aa3b, v111
	v_mul_f32_e32 v104, 0xbfb8aa3b, v104
	v_mul_f32_e32 v105, 0xbfb8aa3b, v105
	v_mul_f32_e32 v106, 0xbfb8aa3b, v106
	v_mul_f32_e32 v107, 0xbfb8aa3b, v107
	v_exp_f32_e32 v108, v108
	v_exp_f32_e32 v109, v109
	v_exp_f32_e32 v110, v110
	v_exp_f32_e32 v111, v111
	v_exp_f32_e32 v104, v104
	v_exp_f32_e32 v105, v105
	v_exp_f32_e32 v106, v106
	v_exp_f32_e32 v107, v107
	v_add_f32_e32 v108, 1.0, v108
	v_add_f32_e32 v109, 1.0, v109
	v_add_f32_e32 v110, 1.0, v110
	v_add_f32_e32 v111, 1.0, v111
	v_add_f32_e32 v104, 1.0, v104
	v_add_f32_e32 v105, 1.0, v105
	v_add_f32_e32 v106, 1.0, v106
	v_add_f32_e32 v107, 1.0, v107
	v_rcp_f32_e32 v108, v108
	v_rcp_f32_e32 v109, v109
	v_rcp_f32_e32 v110, v110
	v_rcp_f32_e32 v111, v111
	v_rcp_f32_e32 v104, v104
	v_rcp_f32_e32 v105, v105
	v_rcp_f32_e32 v106, v106
	v_rcp_f32_e32 v107, v107
	v_fma_f32 v108, v108, v170, v162
	v_fma_f32 v109, v109, v171, v163
	v_fma_f32 v110, v110, v172, v164
	v_fma_f32 v111, v111, v173, v165
	v_fma_f32 v104, v104, v174, v166
	v_fma_f32 v105, v105, v175, v167
	v_fma_f32 v106, v106, v180, v168
	v_fma_f32 v107, v107, v181, v169
	v_mul_f32_e32 v152, v109, v109
	v_mul_f32_e32 v153, v111, v111
	v_mul_f32_e32 v182, v105, v105
	v_mul_f32_e32 v183, v107, v107
	v_fmac_f32_e32 v152, v108, v108
	v_fmac_f32_e32 v153, v110, v110
	v_fmac_f32_e32 v182, v104, v104
	v_fmac_f32_e32 v183, v106, v106
	v_add_f32_e32 v152, v152, v153
	v_add_f32_e32 v182, v182, v183
	v_add_f32_e32 v224, v152, v182
	s_waitcnt lgkmcnt(0)
	v_add_f32_e32 v251, v251, v252
	ds_bpermute_b32 v252, v150, v251
	v_lshlrev_b32_e32 v162, 16, v208
	v_and_b32_e32 v163, 0xffff0000, v208
	v_lshlrev_b32_e32 v170, 16, v212
	v_and_b32_e32 v171, 0xffff0000, v212
	v_lshlrev_b32_e32 v164, 16, v209
	v_and_b32_e32 v165, 0xffff0000, v209
	v_lshlrev_b32_e32 v172, 16, v213
	v_and_b32_e32 v173, 0xffff0000, v213
	v_lshlrev_b32_e32 v166, 16, v210
	v_and_b32_e32 v167, 0xffff0000, v210
	v_lshlrev_b32_e32 v174, 16, v214
	v_and_b32_e32 v175, 0xffff0000, v214
	v_lshlrev_b32_e32 v168, 16, v211
	v_and_b32_e32 v169, 0xffff0000, v211
	v_lshlrev_b32_e32 v180, 16, v215
	v_and_b32_e32 v181, 0xffff0000, v215
	v_mul_f32_e32 v100, v100, v151
	v_mul_f32_e32 v101, v101, v151
	v_mul_f32_e32 v102, v102, v151
	v_mul_f32_e32 v103, v103, v151
	v_mul_f32_e32 v96, v96, v151
	v_mul_f32_e32 v97, v97, v151
	v_mul_f32_e32 v98, v98, v151
	v_mul_f32_e32 v99, v99, v151
	v_mul_f32_e32 v100, 0xbfb8aa3b, v100
	v_mul_f32_e32 v101, 0xbfb8aa3b, v101
	v_mul_f32_e32 v102, 0xbfb8aa3b, v102
	v_mul_f32_e32 v103, 0xbfb8aa3b, v103
	v_mul_f32_e32 v96, 0xbfb8aa3b, v96
	v_mul_f32_e32 v97, 0xbfb8aa3b, v97
	v_mul_f32_e32 v98, 0xbfb8aa3b, v98
	v_mul_f32_e32 v99, 0xbfb8aa3b, v99
	v_exp_f32_e32 v100, v100
	v_exp_f32_e32 v101, v101
	v_exp_f32_e32 v102, v102
	v_exp_f32_e32 v103, v103
	v_exp_f32_e32 v96, v96
	v_exp_f32_e32 v97, v97
	v_exp_f32_e32 v98, v98
	v_exp_f32_e32 v99, v99
	v_add_f32_e32 v100, 1.0, v100
	v_add_f32_e32 v101, 1.0, v101
	v_add_f32_e32 v102, 1.0, v102
	v_add_f32_e32 v103, 1.0, v103
	v_add_f32_e32 v96, 1.0, v96
	v_add_f32_e32 v97, 1.0, v97
	v_add_f32_e32 v98, 1.0, v98
	v_add_f32_e32 v99, 1.0, v99
	v_rcp_f32_e32 v100, v100
	v_rcp_f32_e32 v101, v101
	v_rcp_f32_e32 v102, v102
	v_rcp_f32_e32 v103, v103
	v_rcp_f32_e32 v96, v96
	v_rcp_f32_e32 v97, v97
	v_rcp_f32_e32 v98, v98
	v_rcp_f32_e32 v99, v99
	v_fma_f32 v100, v100, v170, v162
	v_fma_f32 v101, v101, v171, v163
	v_fma_f32 v102, v102, v172, v164
	v_fma_f32 v103, v103, v173, v165
	v_fma_f32 v96, v96, v174, v166
	v_fma_f32 v97, v97, v175, v167
	v_fma_f32 v98, v98, v180, v168
	v_fma_f32 v99, v99, v181, v169
	v_mul_f32_e32 v152, v101, v101
	v_mul_f32_e32 v153, v103, v103
	v_mul_f32_e32 v182, v97, v97
	v_mul_f32_e32 v183, v99, v99
	v_fmac_f32_e32 v152, v100, v100
	v_fmac_f32_e32 v153, v102, v102
	v_fmac_f32_e32 v182, v96, v96
	v_fmac_f32_e32 v183, v98, v98
	v_add_f32_e32 v152, v152, v153
	v_add_f32_e32 v182, v182, v183
	v_add_f32_e32 v250, v152, v182
	s_waitcnt lgkmcnt(0)
	v_add_f32_e32 v253, v251, v252
	s_and_saveexec_b64 s[44:45], s[6:7]
	global_atomic_add_f32 v148, v253, s[16:17] offset:0
	s_or_b64 exec, exec, s[44:45]
	s_add_u32 s48, s12, 0x90000
	s_addc_u32 s49, s13, 0
	s_add_u32 s50, s14, 0x90000
	s_addc_u32 s51, s15, 0
	global_load_dword v177, v148, s[22:23] offset:576
	global_load_dwordx4 v[200:203], v147, s[48:49] offset:0
	global_load_dwordx4 v[204:207], v147, s[50:51] offset:0
	global_load_dwordx4 v[208:211], v147, s[48:49] offset:256
	global_load_dwordx4 v[212:215], v147, s[50:51] offset:256
	v_add_f32_e32 v251, v224, v250
	ds_bpermute_b32 v252, v149, v251
	s_waitcnt vmcnt(16)
	v_fmamk_f32 v151, v178, 0x3a000000, v160
	v_mul_f32_e32 v152, 0x4b800000, v151
	v_cmp_gt_f32_e32 vcc, s65, v151
	s_nop 1
	v_cndmask_b32_e32 v151, v151, v152, vcc
	v_rsq_f32_e32 v151, v151
	s_nop 0
	v_mul_f32_e32 v152, 0x45800000, v151
	v_cndmask_b32_e32 v151, v151, v152, vcc
	v_lshlrev_b32_e32 v162, 16, v216
	v_and_b32_e32 v163, 0xffff0000, v216
	v_lshlrev_b32_e32 v170, 16, v220
	v_and_b32_e32 v171, 0xffff0000, v220
	v_lshlrev_b32_e32 v164, 16, v217
	v_and_b32_e32 v165, 0xffff0000, v217
	v_lshlrev_b32_e32 v172, 16, v221
	v_and_b32_e32 v173, 0xffff0000, v221
	v_lshlrev_b32_e32 v166, 16, v218
	v_and_b32_e32 v167, 0xffff0000, v218
	v_lshlrev_b32_e32 v174, 16, v222
	v_and_b32_e32 v175, 0xffff0000, v222
	v_lshlrev_b32_e32 v168, 16, v219
	v_and_b32_e32 v169, 0xffff0000, v219
	v_lshlrev_b32_e32 v180, 16, v223
	v_and_b32_e32 v181, 0xffff0000, v223
	v_mul_f32_e32 v92, v92, v151
	v_mul_f32_e32 v93, v93, v151
	v_mul_f32_e32 v94, v94, v151
	v_mul_f32_e32 v95, v95, v151
	v_mul_f32_e32 v88, v88, v151
	v_mul_f32_e32 v89, v89, v151
	v_mul_f32_e32 v90, v90, v151
	v_mul_f32_e32 v91, v91, v151
	v_mul_f32_e32 v92, 0xbfb8aa3b, v92
	v_mul_f32_e32 v93, 0xbfb8aa3b, v93
	v_mul_f32_e32 v94, 0xbfb8aa3b, v94
	v_mul_f32_e32 v95, 0xbfb8aa3b, v95
	v_mul_f32_e32 v88, 0xbfb8aa3b, v88
	v_mul_f32_e32 v89, 0xbfb8aa3b, v89
	v_mul_f32_e32 v90, 0xbfb8aa3b, v90
	v_mul_f32_e32 v91, 0xbfb8aa3b, v91
	v_exp_f32_e32 v92, v92
	v_exp_f32_e32 v93, v93
	v_exp_f32_e32 v94, v94
	v_exp_f32_e32 v95, v95
	v_exp_f32_e32 v88, v88
	v_exp_f32_e32 v89, v89
	v_exp_f32_e32 v90, v90
	v_exp_f32_e32 v91, v91
	v_add_f32_e32 v92, 1.0, v92
	v_add_f32_e32 v93, 1.0, v93
	v_add_f32_e32 v94, 1.0, v94
	v_add_f32_e32 v95, 1.0, v95
	v_add_f32_e32 v88, 1.0, v88
	v_add_f32_e32 v89, 1.0, v89
	v_add_f32_e32 v90, 1.0, v90
	v_add_f32_e32 v91, 1.0, v91
	v_rcp_f32_e32 v92, v92
	v_rcp_f32_e32 v93, v93
	v_rcp_f32_e32 v94, v94
	v_rcp_f32_e32 v95, v95
	v_rcp_f32_e32 v88, v88
	v_rcp_f32_e32 v89, v89
	v_rcp_f32_e32 v90, v90
	v_rcp_f32_e32 v91, v91
	v_fma_f32 v92, v92, v170, v162
	v_fma_f32 v93, v93, v171, v163
	v_fma_f32 v94, v94, v172, v164
	v_fma_f32 v95, v95, v173, v165
	v_fma_f32 v88, v88, v174, v166
	v_fma_f32 v89, v89, v175, v167
	v_fma_f32 v90, v90, v180, v168
	v_fma_f32 v91, v91, v181, v169
	v_mul_f32_e32 v152, v93, v93
	v_mul_f32_e32 v153, v95, v95
	v_mul_f32_e32 v182, v89, v89
	v_mul_f32_e32 v183, v91, v91
	v_fmac_f32_e32 v152, v92, v92
	v_fmac_f32_e32 v153, v94, v94
	v_fmac_f32_e32 v182, v88, v88
	v_fmac_f32_e32 v183, v90, v90
	v_add_f32_e32 v152, v152, v153
	v_add_f32_e32 v182, v182, v183
	v_add_f32_e32 v224, v152, v182
	s_waitcnt lgkmcnt(0)
	v_add_f32_e32 v251, v251, v252
	ds_bpermute_b32 v252, v150, v251
	v_lshlrev_b32_e32 v162, 16, v226
	v_and_b32_e32 v163, 0xffff0000, v226
	v_lshlrev_b32_e32 v170, 16, v230
	v_and_b32_e32 v171, 0xffff0000, v230
	v_lshlrev_b32_e32 v164, 16, v227
	v_and_b32_e32 v165, 0xffff0000, v227
	v_lshlrev_b32_e32 v172, 16, v231
	v_and_b32_e32 v173, 0xffff0000, v231
	v_lshlrev_b32_e32 v166, 16, v228
	v_and_b32_e32 v167, 0xffff0000, v228
	v_lshlrev_b32_e32 v174, 16, v232
	v_and_b32_e32 v175, 0xffff0000, v232
	v_lshlrev_b32_e32 v168, 16, v229
	v_and_b32_e32 v169, 0xffff0000, v229
	v_lshlrev_b32_e32 v180, 16, v233
	v_and_b32_e32 v181, 0xffff0000, v233
	v_mul_f32_e32 v84, v84, v151
	v_mul_f32_e32 v85, v85, v151
	v_mul_f32_e32 v86, v86, v151
	v_mul_f32_e32 v87, v87, v151
	v_mul_f32_e32 v80, v80, v151
	v_mul_f32_e32 v81, v81, v151
	v_mul_f32_e32 v82, v82, v151
	v_mul_f32_e32 v83, v83, v151
	v_mul_f32_e32 v84, 0xbfb8aa3b, v84
	v_mul_f32_e32 v85, 0xbfb8aa3b, v85
	v_mul_f32_e32 v86, 0xbfb8aa3b, v86
	v_mul_f32_e32 v87, 0xbfb8aa3b, v87
	v_mul_f32_e32 v80, 0xbfb8aa3b, v80
	v_mul_f32_e32 v81, 0xbfb8aa3b, v81
	v_mul_f32_e32 v82, 0xbfb8aa3b, v82
	v_mul_f32_e32 v83, 0xbfb8aa3b, v83
	v_exp_f32_e32 v84, v84
	v_exp_f32_e32 v85, v85
	v_exp_f32_e32 v86, v86
	v_exp_f32_e32 v87, v87
	v_exp_f32_e32 v80, v80
	v_exp_f32_e32 v81, v81
	v_exp_f32_e32 v82, v82
	v_exp_f32_e32 v83, v83
	v_add_f32_e32 v84, 1.0, v84
	v_add_f32_e32 v85, 1.0, v85
	v_add_f32_e32 v86, 1.0, v86
	v_add_f32_e32 v87, 1.0, v87
	v_add_f32_e32 v80, 1.0, v80
	v_add_f32_e32 v81, 1.0, v81
	v_add_f32_e32 v82, 1.0, v82
	v_add_f32_e32 v83, 1.0, v83
	v_rcp_f32_e32 v84, v84
	v_rcp_f32_e32 v85, v85
	v_rcp_f32_e32 v86, v86
	v_rcp_f32_e32 v87, v87
	v_rcp_f32_e32 v80, v80
	v_rcp_f32_e32 v81, v81
	v_rcp_f32_e32 v82, v82
	v_rcp_f32_e32 v83, v83
	v_fma_f32 v84, v84, v170, v162
	v_fma_f32 v85, v85, v171, v163
	v_fma_f32 v86, v86, v172, v164
	v_fma_f32 v87, v87, v173, v165
	v_fma_f32 v80, v80, v174, v166
	v_fma_f32 v81, v81, v175, v167
	v_fma_f32 v82, v82, v180, v168
	v_fma_f32 v83, v83, v181, v169
	v_mul_f32_e32 v152, v85, v85
	v_mul_f32_e32 v153, v87, v87
	v_mul_f32_e32 v182, v81, v81
	v_mul_f32_e32 v183, v83, v83
	v_fmac_f32_e32 v152, v84, v84
	v_fmac_f32_e32 v153, v86, v86
	v_fmac_f32_e32 v182, v80, v80
	v_fmac_f32_e32 v183, v82, v82
	v_add_f32_e32 v152, v152, v153
	v_add_f32_e32 v182, v182, v183
	v_add_f32_e32 v250, v152, v182
	s_waitcnt lgkmcnt(0)
	v_add_f32_e32 v253, v251, v252
	s_and_saveexec_b64 s[44:45], s[6:7]
	global_atomic_add_f32 v148, v253, s[16:17] offset:64
	s_or_b64 exec, exec, s[44:45]
	s_add_u32 s48, s12, 0xa0000
	s_addc_u32 s49, s13, 0
	s_add_u32 s50, s14, 0xa0000
	s_addc_u32 s51, s15, 0
	global_load_dword v178, v148, s[22:23] offset:640
	global_load_dwordx4 v[216:219], v147, s[48:49] offset:0
	global_load_dwordx4 v[220:223], v147, s[50:51] offset:0
	global_load_dwordx4 v[226:229], v147, s[48:49] offset:256
	global_load_dwordx4 v[230:233], v147, s[50:51] offset:256
	v_add_f32_e32 v251, v224, v250
	ds_bpermute_b32 v252, v149, v251
	s_waitcnt vmcnt(17)
	v_fmamk_f32 v151, v179, 0x3a000000, v160
	v_mul_f32_e32 v152, 0x4b800000, v151
	v_cmp_gt_f32_e32 vcc, s65, v151
	s_nop 1
	v_cndmask_b32_e32 v151, v151, v152, vcc
	v_rsq_f32_e32 v151, v151
	s_nop 0
	v_mul_f32_e32 v152, 0x45800000, v151
	v_cndmask_b32_e32 v151, v151, v152, vcc
	v_lshlrev_b32_e32 v162, 16, v234
	v_and_b32_e32 v163, 0xffff0000, v234
	v_lshlrev_b32_e32 v170, 16, v238
	v_and_b32_e32 v171, 0xffff0000, v238
	v_lshlrev_b32_e32 v164, 16, v235
	v_and_b32_e32 v165, 0xffff0000, v235
	v_lshlrev_b32_e32 v172, 16, v239
	v_and_b32_e32 v173, 0xffff0000, v239
	v_lshlrev_b32_e32 v166, 16, v236
	v_and_b32_e32 v167, 0xffff0000, v236
	v_lshlrev_b32_e32 v174, 16, v240
	v_and_b32_e32 v175, 0xffff0000, v240
	v_lshlrev_b32_e32 v168, 16, v237
	v_and_b32_e32 v169, 0xffff0000, v237
	v_lshlrev_b32_e32 v180, 16, v241
	v_and_b32_e32 v181, 0xffff0000, v241
	v_mul_f32_e32 v76, v76, v151
	v_mul_f32_e32 v77, v77, v151
	v_mul_f32_e32 v78, v78, v151
	v_mul_f32_e32 v79, v79, v151
	v_mul_f32_e32 v72, v72, v151
	v_mul_f32_e32 v73, v73, v151
	v_mul_f32_e32 v74, v74, v151
	v_mul_f32_e32 v75, v75, v151
	v_mul_f32_e32 v76, 0xbfb8aa3b, v76
	v_mul_f32_e32 v77, 0xbfb8aa3b, v77
	v_mul_f32_e32 v78, 0xbfb8aa3b, v78
	v_mul_f32_e32 v79, 0xbfb8aa3b, v79
	v_mul_f32_e32 v72, 0xbfb8aa3b, v72
	v_mul_f32_e32 v73, 0xbfb8aa3b, v73
	v_mul_f32_e32 v74, 0xbfb8aa3b, v74
	v_mul_f32_e32 v75, 0xbfb8aa3b, v75
	v_exp_f32_e32 v76, v76
	v_exp_f32_e32 v77, v77
	v_exp_f32_e32 v78, v78
	v_exp_f32_e32 v79, v79
	v_exp_f32_e32 v72, v72
	v_exp_f32_e32 v73, v73
	v_exp_f32_e32 v74, v74
	v_exp_f32_e32 v75, v75
	v_add_f32_e32 v76, 1.0, v76
	v_add_f32_e32 v77, 1.0, v77
	v_add_f32_e32 v78, 1.0, v78
	v_add_f32_e32 v79, 1.0, v79
	v_add_f32_e32 v72, 1.0, v72
	v_add_f32_e32 v73, 1.0, v73
	v_add_f32_e32 v74, 1.0, v74
	v_add_f32_e32 v75, 1.0, v75
	v_rcp_f32_e32 v76, v76
	v_rcp_f32_e32 v77, v77
	v_rcp_f32_e32 v78, v78
	v_rcp_f32_e32 v79, v79
	v_rcp_f32_e32 v72, v72
	v_rcp_f32_e32 v73, v73
	v_rcp_f32_e32 v74, v74
	v_rcp_f32_e32 v75, v75
	v_fma_f32 v76, v76, v170, v162
	v_fma_f32 v77, v77, v171, v163
	v_fma_f32 v78, v78, v172, v164
	v_fma_f32 v79, v79, v173, v165
	v_fma_f32 v72, v72, v174, v166
	v_fma_f32 v73, v73, v175, v167
	v_fma_f32 v74, v74, v180, v168
	v_fma_f32 v75, v75, v181, v169
	v_mul_f32_e32 v152, v77, v77
	v_mul_f32_e32 v153, v79, v79
	v_mul_f32_e32 v182, v73, v73
	v_mul_f32_e32 v183, v75, v75
	v_fmac_f32_e32 v152, v76, v76
	v_fmac_f32_e32 v153, v78, v78
	v_fmac_f32_e32 v182, v72, v72
	v_fmac_f32_e32 v183, v74, v74
	v_add_f32_e32 v152, v152, v153
	v_add_f32_e32 v182, v182, v183
	v_add_f32_e32 v224, v152, v182
	s_waitcnt lgkmcnt(0)
	v_add_f32_e32 v251, v251, v252
	ds_bpermute_b32 v252, v150, v251
	v_lshlrev_b32_e32 v162, 16, v242
	v_and_b32_e32 v163, 0xffff0000, v242
	v_lshlrev_b32_e32 v170, 16, v246
	v_and_b32_e32 v171, 0xffff0000, v246
	v_lshlrev_b32_e32 v164, 16, v243
	v_and_b32_e32 v165, 0xffff0000, v243
	v_lshlrev_b32_e32 v172, 16, v247
	v_and_b32_e32 v173, 0xffff0000, v247
	v_lshlrev_b32_e32 v166, 16, v244
	v_and_b32_e32 v167, 0xffff0000, v244
	v_lshlrev_b32_e32 v174, 16, v248
	v_and_b32_e32 v175, 0xffff0000, v248
	v_lshlrev_b32_e32 v168, 16, v245
	v_and_b32_e32 v169, 0xffff0000, v245
	v_lshlrev_b32_e32 v180, 16, v249
	v_and_b32_e32 v181, 0xffff0000, v249
	v_mul_f32_e32 v68, v68, v151
	v_mul_f32_e32 v69, v69, v151
	v_mul_f32_e32 v70, v70, v151
	v_mul_f32_e32 v71, v71, v151
	v_mul_f32_e32 v64, v64, v151
	v_mul_f32_e32 v65, v65, v151
	v_mul_f32_e32 v66, v66, v151
	v_mul_f32_e32 v67, v67, v151
	v_mul_f32_e32 v68, 0xbfb8aa3b, v68
	v_mul_f32_e32 v69, 0xbfb8aa3b, v69
	v_mul_f32_e32 v70, 0xbfb8aa3b, v70
	v_mul_f32_e32 v71, 0xbfb8aa3b, v71
	v_mul_f32_e32 v64, 0xbfb8aa3b, v64
	v_mul_f32_e32 v65, 0xbfb8aa3b, v65
	v_mul_f32_e32 v66, 0xbfb8aa3b, v66
	v_mul_f32_e32 v67, 0xbfb8aa3b, v67
	v_exp_f32_e32 v68, v68
	v_exp_f32_e32 v69, v69
	v_exp_f32_e32 v70, v70
	v_exp_f32_e32 v71, v71
	v_exp_f32_e32 v64, v64
	v_exp_f32_e32 v65, v65
	v_exp_f32_e32 v66, v66
	v_exp_f32_e32 v67, v67
	v_add_f32_e32 v68, 1.0, v68
	v_add_f32_e32 v69, 1.0, v69
	v_add_f32_e32 v70, 1.0, v70
	v_add_f32_e32 v71, 1.0, v71
	v_add_f32_e32 v64, 1.0, v64
	v_add_f32_e32 v65, 1.0, v65
	v_add_f32_e32 v66, 1.0, v66
	v_add_f32_e32 v67, 1.0, v67
	v_rcp_f32_e32 v68, v68
	v_rcp_f32_e32 v69, v69
	v_rcp_f32_e32 v70, v70
	v_rcp_f32_e32 v71, v71
	v_rcp_f32_e32 v64, v64
	v_rcp_f32_e32 v65, v65
	v_rcp_f32_e32 v66, v66
	v_rcp_f32_e32 v67, v67
	v_fma_f32 v68, v68, v170, v162
	v_fma_f32 v69, v69, v171, v163
	v_fma_f32 v70, v70, v172, v164
	v_fma_f32 v71, v71, v173, v165
	v_fma_f32 v64, v64, v174, v166
	v_fma_f32 v65, v65, v175, v167
	v_fma_f32 v66, v66, v180, v168
	v_fma_f32 v67, v67, v181, v169
	v_mul_f32_e32 v152, v69, v69
	v_mul_f32_e32 v153, v71, v71
	v_mul_f32_e32 v182, v65, v65
	v_mul_f32_e32 v183, v67, v67
	v_fmac_f32_e32 v152, v68, v68
	v_fmac_f32_e32 v153, v70, v70
	v_fmac_f32_e32 v182, v64, v64
	v_fmac_f32_e32 v183, v66, v66
	v_add_f32_e32 v152, v152, v153
	v_add_f32_e32 v182, v182, v183
	v_add_f32_e32 v250, v152, v182
	s_waitcnt lgkmcnt(0)
	v_add_f32_e32 v253, v251, v252
	s_and_saveexec_b64 s[44:45], s[6:7]
	global_atomic_add_f32 v148, v253, s[16:17] offset:128
	s_or_b64 exec, exec, s[44:45]
	s_add_u32 s48, s12, 0xb0000
	s_addc_u32 s49, s13, 0
	s_add_u32 s50, s14, 0xb0000
	s_addc_u32 s51, s15, 0
	global_load_dword v179, v148, s[22:23] offset:704
	global_load_dwordx4 v[234:237], v147, s[48:49] offset:0
	global_load_dwordx4 v[238:241], v147, s[50:51] offset:0
	global_load_dwordx4 v[242:245], v147, s[48:49] offset:256
	global_load_dwordx4 v[246:249], v147, s[50:51] offset:256
	v_add_f32_e32 v251, v224, v250
	ds_bpermute_b32 v252, v149, v251
	s_waitcnt vmcnt(18)
	v_fmamk_f32 v151, v176, 0x3a000000, v160
	v_mul_f32_e32 v152, 0x4b800000, v151
	v_cmp_gt_f32_e32 vcc, s65, v151
	s_nop 1
	v_cndmask_b32_e32 v151, v151, v152, vcc
	v_rsq_f32_e32 v151, v151
	s_nop 0
	v_mul_f32_e32 v152, 0x45800000, v151
	v_cndmask_b32_e32 v151, v151, v152, vcc
	v_lshlrev_b32_e32 v162, 16, v184
	v_and_b32_e32 v163, 0xffff0000, v184
	v_lshlrev_b32_e32 v170, 16, v188
	v_and_b32_e32 v171, 0xffff0000, v188
	v_lshlrev_b32_e32 v164, 16, v185
	v_and_b32_e32 v165, 0xffff0000, v185
	v_lshlrev_b32_e32 v172, 16, v189
	v_and_b32_e32 v173, 0xffff0000, v189
	v_lshlrev_b32_e32 v166, 16, v186
	v_and_b32_e32 v167, 0xffff0000, v186
	v_lshlrev_b32_e32 v174, 16, v190
	v_and_b32_e32 v175, 0xffff0000, v190
	v_lshlrev_b32_e32 v168, 16, v187
	v_and_b32_e32 v169, 0xffff0000, v187
	v_lshlrev_b32_e32 v180, 16, v191
	v_and_b32_e32 v181, 0xffff0000, v191
	v_mul_f32_e32 v60, v60, v151
	v_mul_f32_e32 v61, v61, v151
	v_mul_f32_e32 v62, v62, v151
	v_mul_f32_e32 v63, v63, v151
	v_mul_f32_e32 v56, v56, v151
	v_mul_f32_e32 v57, v57, v151
	v_mul_f32_e32 v58, v58, v151
	v_mul_f32_e32 v59, v59, v151
	v_mul_f32_e32 v60, 0xbfb8aa3b, v60
	v_mul_f32_e32 v61, 0xbfb8aa3b, v61
	v_mul_f32_e32 v62, 0xbfb8aa3b, v62
	v_mul_f32_e32 v63, 0xbfb8aa3b, v63
	v_mul_f32_e32 v56, 0xbfb8aa3b, v56
	v_mul_f32_e32 v57, 0xbfb8aa3b, v57
	v_mul_f32_e32 v58, 0xbfb8aa3b, v58
	v_mul_f32_e32 v59, 0xbfb8aa3b, v59
	v_exp_f32_e32 v60, v60
	v_exp_f32_e32 v61, v61
	v_exp_f32_e32 v62, v62
	v_exp_f32_e32 v63, v63
	v_exp_f32_e32 v56, v56
	v_exp_f32_e32 v57, v57
	v_exp_f32_e32 v58, v58
	v_exp_f32_e32 v59, v59
	v_add_f32_e32 v60, 1.0, v60
	v_add_f32_e32 v61, 1.0, v61
	v_add_f32_e32 v62, 1.0, v62
	v_add_f32_e32 v63, 1.0, v63
	v_add_f32_e32 v56, 1.0, v56
	v_add_f32_e32 v57, 1.0, v57
	v_add_f32_e32 v58, 1.0, v58
	v_add_f32_e32 v59, 1.0, v59
	v_rcp_f32_e32 v60, v60
	v_rcp_f32_e32 v61, v61
	v_rcp_f32_e32 v62, v62
	v_rcp_f32_e32 v63, v63
	v_rcp_f32_e32 v56, v56
	v_rcp_f32_e32 v57, v57
	v_rcp_f32_e32 v58, v58
	v_rcp_f32_e32 v59, v59
	v_fma_f32 v60, v60, v170, v162
	v_fma_f32 v61, v61, v171, v163
	v_fma_f32 v62, v62, v172, v164
	v_fma_f32 v63, v63, v173, v165
	v_fma_f32 v56, v56, v174, v166
	v_fma_f32 v57, v57, v175, v167
	v_fma_f32 v58, v58, v180, v168
	v_fma_f32 v59, v59, v181, v169
	v_mul_f32_e32 v152, v61, v61
	v_mul_f32_e32 v153, v63, v63
	v_mul_f32_e32 v182, v57, v57
	v_mul_f32_e32 v183, v59, v59
	v_fmac_f32_e32 v152, v60, v60
	v_fmac_f32_e32 v153, v62, v62
	v_fmac_f32_e32 v182, v56, v56
	v_fmac_f32_e32 v183, v58, v58
	v_add_f32_e32 v152, v152, v153
	v_add_f32_e32 v182, v182, v183
	v_add_f32_e32 v224, v152, v182
	s_waitcnt lgkmcnt(0)
	v_add_f32_e32 v251, v251, v252
	ds_bpermute_b32 v252, v150, v251
	v_lshlrev_b32_e32 v162, 16, v192
	v_and_b32_e32 v163, 0xffff0000, v192
	v_lshlrev_b32_e32 v170, 16, v196
	v_and_b32_e32 v171, 0xffff0000, v196
	v_lshlrev_b32_e32 v164, 16, v193
	v_and_b32_e32 v165, 0xffff0000, v193
	v_lshlrev_b32_e32 v172, 16, v197
	v_and_b32_e32 v173, 0xffff0000, v197
	v_lshlrev_b32_e32 v166, 16, v194
	v_and_b32_e32 v167, 0xffff0000, v194
	v_lshlrev_b32_e32 v174, 16, v198
	v_and_b32_e32 v175, 0xffff0000, v198
	v_lshlrev_b32_e32 v168, 16, v195
	v_and_b32_e32 v169, 0xffff0000, v195
	v_lshlrev_b32_e32 v180, 16, v199
	v_and_b32_e32 v181, 0xffff0000, v199
	v_mul_f32_e32 v52, v52, v151
	v_mul_f32_e32 v53, v53, v151
	v_mul_f32_e32 v54, v54, v151
	v_mul_f32_e32 v55, v55, v151
	v_mul_f32_e32 v48, v48, v151
	v_mul_f32_e32 v49, v49, v151
	v_mul_f32_e32 v50, v50, v151
	v_mul_f32_e32 v51, v51, v151
	v_mul_f32_e32 v52, 0xbfb8aa3b, v52
	v_mul_f32_e32 v53, 0xbfb8aa3b, v53
	v_mul_f32_e32 v54, 0xbfb8aa3b, v54
	v_mul_f32_e32 v55, 0xbfb8aa3b, v55
	v_mul_f32_e32 v48, 0xbfb8aa3b, v48
	v_mul_f32_e32 v49, 0xbfb8aa3b, v49
	v_mul_f32_e32 v50, 0xbfb8aa3b, v50
	v_mul_f32_e32 v51, 0xbfb8aa3b, v51
	v_exp_f32_e32 v52, v52
	v_exp_f32_e32 v53, v53
	v_exp_f32_e32 v54, v54
	v_exp_f32_e32 v55, v55
	v_exp_f32_e32 v48, v48
	v_exp_f32_e32 v49, v49
	v_exp_f32_e32 v50, v50
	v_exp_f32_e32 v51, v51
	v_add_f32_e32 v52, 1.0, v52
	v_add_f32_e32 v53, 1.0, v53
	v_add_f32_e32 v54, 1.0, v54
	v_add_f32_e32 v55, 1.0, v55
	v_add_f32_e32 v48, 1.0, v48
	v_add_f32_e32 v49, 1.0, v49
	v_add_f32_e32 v50, 1.0, v50
	v_add_f32_e32 v51, 1.0, v51
	v_rcp_f32_e32 v52, v52
	v_rcp_f32_e32 v53, v53
	v_rcp_f32_e32 v54, v54
	v_rcp_f32_e32 v55, v55
	v_rcp_f32_e32 v48, v48
	v_rcp_f32_e32 v49, v49
	v_rcp_f32_e32 v50, v50
	v_rcp_f32_e32 v51, v51
	v_fma_f32 v52, v52, v170, v162
	v_fma_f32 v53, v53, v171, v163
	v_fma_f32 v54, v54, v172, v164
	v_fma_f32 v55, v55, v173, v165
	v_fma_f32 v48, v48, v174, v166
	v_fma_f32 v49, v49, v175, v167
	v_fma_f32 v50, v50, v180, v168
	v_fma_f32 v51, v51, v181, v169
	v_mul_f32_e32 v152, v53, v53
	v_mul_f32_e32 v153, v55, v55
	v_mul_f32_e32 v182, v49, v49
	v_mul_f32_e32 v183, v51, v51
	v_fmac_f32_e32 v152, v52, v52
	v_fmac_f32_e32 v153, v54, v54
	v_fmac_f32_e32 v182, v48, v48
	v_fmac_f32_e32 v183, v50, v50
	v_add_f32_e32 v152, v152, v153
	v_add_f32_e32 v182, v182, v183
	v_add_f32_e32 v250, v152, v182
	s_waitcnt lgkmcnt(0)
	v_add_f32_e32 v253, v251, v252
	s_and_saveexec_b64 s[44:45], s[6:7]
	global_atomic_add_f32 v148, v253, s[16:17] offset:192
	s_or_b64 exec, exec, s[44:45]
	v_add_f32_e32 v251, v224, v250
	ds_bpermute_b32 v252, v149, v251
	s_waitcnt vmcnt(13)
	v_fmamk_f32 v151, v177, 0x3a000000, v160
	v_mul_f32_e32 v152, 0x4b800000, v151
	v_cmp_gt_f32_e32 vcc, s65, v151
	s_nop 1
	v_cndmask_b32_e32 v151, v151, v152, vcc
	v_rsq_f32_e32 v151, v151
	s_nop 0
	v_mul_f32_e32 v152, 0x45800000, v151
	v_cndmask_b32_e32 v151, v151, v152, vcc
	v_lshlrev_b32_e32 v162, 16, v200
	v_and_b32_e32 v163, 0xffff0000, v200
	v_lshlrev_b32_e32 v170, 16, v204
	v_and_b32_e32 v171, 0xffff0000, v204
	v_lshlrev_b32_e32 v164, 16, v201
	v_and_b32_e32 v165, 0xffff0000, v201
	v_lshlrev_b32_e32 v172, 16, v205
	v_and_b32_e32 v173, 0xffff0000, v205
	v_lshlrev_b32_e32 v166, 16, v202
	v_and_b32_e32 v167, 0xffff0000, v202
	v_lshlrev_b32_e32 v174, 16, v206
	v_and_b32_e32 v175, 0xffff0000, v206
	v_lshlrev_b32_e32 v168, 16, v203
	v_and_b32_e32 v169, 0xffff0000, v203
	v_lshlrev_b32_e32 v180, 16, v207
	v_and_b32_e32 v181, 0xffff0000, v207
	v_mul_f32_e32 v44, v44, v151
	v_mul_f32_e32 v45, v45, v151
	v_mul_f32_e32 v46, v46, v151
	v_mul_f32_e32 v47, v47, v151
	v_mul_f32_e32 v40, v40, v151
	v_mul_f32_e32 v41, v41, v151
	v_mul_f32_e32 v42, v42, v151
	v_mul_f32_e32 v43, v43, v151
	v_mul_f32_e32 v44, 0xbfb8aa3b, v44
	v_mul_f32_e32 v45, 0xbfb8aa3b, v45
	v_mul_f32_e32 v46, 0xbfb8aa3b, v46
	v_mul_f32_e32 v47, 0xbfb8aa3b, v47
	v_mul_f32_e32 v40, 0xbfb8aa3b, v40
	v_mul_f32_e32 v41, 0xbfb8aa3b, v41
	v_mul_f32_e32 v42, 0xbfb8aa3b, v42
	v_mul_f32_e32 v43, 0xbfb8aa3b, v43
	v_exp_f32_e32 v44, v44
	v_exp_f32_e32 v45, v45
	v_exp_f32_e32 v46, v46
	v_exp_f32_e32 v47, v47
	v_exp_f32_e32 v40, v40
	v_exp_f32_e32 v41, v41
	v_exp_f32_e32 v42, v42
	v_exp_f32_e32 v43, v43
	v_add_f32_e32 v44, 1.0, v44
	v_add_f32_e32 v45, 1.0, v45
	v_add_f32_e32 v46, 1.0, v46
	v_add_f32_e32 v47, 1.0, v47
	v_add_f32_e32 v40, 1.0, v40
	v_add_f32_e32 v41, 1.0, v41
	v_add_f32_e32 v42, 1.0, v42
	v_add_f32_e32 v43, 1.0, v43
	v_rcp_f32_e32 v44, v44
	v_rcp_f32_e32 v45, v45
	v_rcp_f32_e32 v46, v46
	v_rcp_f32_e32 v47, v47
	v_rcp_f32_e32 v40, v40
	v_rcp_f32_e32 v41, v41
	v_rcp_f32_e32 v42, v42
	v_rcp_f32_e32 v43, v43
	v_fma_f32 v44, v44, v170, v162
	v_fma_f32 v45, v45, v171, v163
	v_fma_f32 v46, v46, v172, v164
	v_fma_f32 v47, v47, v173, v165
	v_fma_f32 v40, v40, v174, v166
	v_fma_f32 v41, v41, v175, v167
	v_fma_f32 v42, v42, v180, v168
	v_fma_f32 v43, v43, v181, v169
	v_mul_f32_e32 v152, v45, v45
	v_mul_f32_e32 v153, v47, v47
	v_mul_f32_e32 v182, v41, v41
	v_mul_f32_e32 v183, v43, v43
	v_fmac_f32_e32 v152, v44, v44
	v_fmac_f32_e32 v153, v46, v46
	v_fmac_f32_e32 v182, v40, v40
	v_fmac_f32_e32 v183, v42, v42
	v_add_f32_e32 v152, v152, v153
	v_add_f32_e32 v182, v182, v183
	v_add_f32_e32 v224, v152, v182
	s_waitcnt lgkmcnt(0)
	v_add_f32_e32 v251, v251, v252
	ds_bpermute_b32 v252, v150, v251
	v_lshlrev_b32_e32 v162, 16, v208
	v_and_b32_e32 v163, 0xffff0000, v208
	v_lshlrev_b32_e32 v170, 16, v212
	v_and_b32_e32 v171, 0xffff0000, v212
	v_lshlrev_b32_e32 v164, 16, v209
	v_and_b32_e32 v165, 0xffff0000, v209
	v_lshlrev_b32_e32 v172, 16, v213
	v_and_b32_e32 v173, 0xffff0000, v213
	v_lshlrev_b32_e32 v166, 16, v210
	v_and_b32_e32 v167, 0xffff0000, v210
	v_lshlrev_b32_e32 v174, 16, v214
	v_and_b32_e32 v175, 0xffff0000, v214
	v_lshlrev_b32_e32 v168, 16, v211
	v_and_b32_e32 v169, 0xffff0000, v211
	v_lshlrev_b32_e32 v180, 16, v215
	v_and_b32_e32 v181, 0xffff0000, v215
	v_mul_f32_e32 v36, v36, v151
	v_mul_f32_e32 v37, v37, v151
	v_mul_f32_e32 v38, v38, v151
	v_mul_f32_e32 v39, v39, v151
	v_mul_f32_e32 v32, v32, v151
	v_mul_f32_e32 v33, v33, v151
	v_mul_f32_e32 v34, v34, v151
	v_mul_f32_e32 v35, v35, v151
	v_mul_f32_e32 v36, 0xbfb8aa3b, v36
	v_mul_f32_e32 v37, 0xbfb8aa3b, v37
	v_mul_f32_e32 v38, 0xbfb8aa3b, v38
	v_mul_f32_e32 v39, 0xbfb8aa3b, v39
	v_mul_f32_e32 v32, 0xbfb8aa3b, v32
	v_mul_f32_e32 v33, 0xbfb8aa3b, v33
	v_mul_f32_e32 v34, 0xbfb8aa3b, v34
	v_mul_f32_e32 v35, 0xbfb8aa3b, v35
	v_exp_f32_e32 v36, v36
	v_exp_f32_e32 v37, v37
	v_exp_f32_e32 v38, v38
	v_exp_f32_e32 v39, v39
	v_exp_f32_e32 v32, v32
	v_exp_f32_e32 v33, v33
	v_exp_f32_e32 v34, v34
	v_exp_f32_e32 v35, v35
	v_add_f32_e32 v36, 1.0, v36
	v_add_f32_e32 v37, 1.0, v37
	v_add_f32_e32 v38, 1.0, v38
	v_add_f32_e32 v39, 1.0, v39
	v_add_f32_e32 v32, 1.0, v32
	v_add_f32_e32 v33, 1.0, v33
	v_add_f32_e32 v34, 1.0, v34
	v_add_f32_e32 v35, 1.0, v35
	v_rcp_f32_e32 v36, v36
	v_rcp_f32_e32 v37, v37
	v_rcp_f32_e32 v38, v38
	v_rcp_f32_e32 v39, v39
	v_rcp_f32_e32 v32, v32
	v_rcp_f32_e32 v33, v33
	v_rcp_f32_e32 v34, v34
	v_rcp_f32_e32 v35, v35
	v_fma_f32 v36, v36, v170, v162
	v_fma_f32 v37, v37, v171, v163
	v_fma_f32 v38, v38, v172, v164
	v_fma_f32 v39, v39, v173, v165
	v_fma_f32 v32, v32, v174, v166
	v_fma_f32 v33, v33, v175, v167
	v_fma_f32 v34, v34, v180, v168
	v_fma_f32 v35, v35, v181, v169
	v_mul_f32_e32 v152, v37, v37
	v_mul_f32_e32 v153, v39, v39
	v_mul_f32_e32 v182, v33, v33
	v_mul_f32_e32 v183, v35, v35
	v_fmac_f32_e32 v152, v36, v36
	v_fmac_f32_e32 v153, v38, v38
	v_fmac_f32_e32 v182, v32, v32
	v_fmac_f32_e32 v183, v34, v34
	v_add_f32_e32 v152, v152, v153
	v_add_f32_e32 v182, v182, v183
	v_add_f32_e32 v250, v152, v182
	s_waitcnt lgkmcnt(0)
	v_add_f32_e32 v253, v251, v252
	s_and_saveexec_b64 s[44:45], s[6:7]
	global_atomic_add_f32 v148, v253, s[16:17] offset:512
	s_or_b64 exec, exec, s[44:45]
	v_add_f32_e32 v251, v224, v250
	ds_bpermute_b32 v252, v149, v251
	s_waitcnt vmcnt(8)
	v_fmamk_f32 v151, v178, 0x3a000000, v160
	v_mul_f32_e32 v152, 0x4b800000, v151
	v_cmp_gt_f32_e32 vcc, s65, v151
	s_nop 1
	v_cndmask_b32_e32 v151, v151, v152, vcc
	v_rsq_f32_e32 v151, v151
	s_nop 0
	v_mul_f32_e32 v152, 0x45800000, v151
	v_cndmask_b32_e32 v151, v151, v152, vcc
	v_lshlrev_b32_e32 v162, 16, v216
	v_and_b32_e32 v163, 0xffff0000, v216
	v_lshlrev_b32_e32 v170, 16, v220
	v_and_b32_e32 v171, 0xffff0000, v220
	v_lshlrev_b32_e32 v164, 16, v217
	v_and_b32_e32 v165, 0xffff0000, v217
	v_lshlrev_b32_e32 v172, 16, v221
	v_and_b32_e32 v173, 0xffff0000, v221
	v_lshlrev_b32_e32 v166, 16, v218
	v_and_b32_e32 v167, 0xffff0000, v218
	v_lshlrev_b32_e32 v174, 16, v222
	v_and_b32_e32 v175, 0xffff0000, v222
	v_lshlrev_b32_e32 v168, 16, v219
	v_and_b32_e32 v169, 0xffff0000, v219
	v_lshlrev_b32_e32 v180, 16, v223
	v_and_b32_e32 v181, 0xffff0000, v223
	v_mul_f32_e32 v28, v28, v151
	v_mul_f32_e32 v29, v29, v151
	v_mul_f32_e32 v30, v30, v151
	v_mul_f32_e32 v31, v31, v151
	v_mul_f32_e32 v24, v24, v151
	v_mul_f32_e32 v25, v25, v151
	v_mul_f32_e32 v26, v26, v151
	v_mul_f32_e32 v27, v27, v151
	v_mul_f32_e32 v28, 0xbfb8aa3b, v28
	v_mul_f32_e32 v29, 0xbfb8aa3b, v29
	v_mul_f32_e32 v30, 0xbfb8aa3b, v30
	v_mul_f32_e32 v31, 0xbfb8aa3b, v31
	v_mul_f32_e32 v24, 0xbfb8aa3b, v24
	v_mul_f32_e32 v25, 0xbfb8aa3b, v25
	v_mul_f32_e32 v26, 0xbfb8aa3b, v26
	v_mul_f32_e32 v27, 0xbfb8aa3b, v27
	v_exp_f32_e32 v28, v28
	v_exp_f32_e32 v29, v29
	v_exp_f32_e32 v30, v30
	v_exp_f32_e32 v31, v31
	v_exp_f32_e32 v24, v24
	v_exp_f32_e32 v25, v25
	v_exp_f32_e32 v26, v26
	v_exp_f32_e32 v27, v27
	v_add_f32_e32 v28, 1.0, v28
	v_add_f32_e32 v29, 1.0, v29
	v_add_f32_e32 v30, 1.0, v30
	v_add_f32_e32 v31, 1.0, v31
	v_add_f32_e32 v24, 1.0, v24
	v_add_f32_e32 v25, 1.0, v25
	v_add_f32_e32 v26, 1.0, v26
	v_add_f32_e32 v27, 1.0, v27
	v_rcp_f32_e32 v28, v28
	v_rcp_f32_e32 v29, v29
	v_rcp_f32_e32 v30, v30
	v_rcp_f32_e32 v31, v31
	v_rcp_f32_e32 v24, v24
	v_rcp_f32_e32 v25, v25
	v_rcp_f32_e32 v26, v26
	v_rcp_f32_e32 v27, v27
	v_fma_f32 v28, v28, v170, v162
	v_fma_f32 v29, v29, v171, v163
	v_fma_f32 v30, v30, v172, v164
	v_fma_f32 v31, v31, v173, v165
	v_fma_f32 v24, v24, v174, v166
	v_fma_f32 v25, v25, v175, v167
	v_fma_f32 v26, v26, v180, v168
	v_fma_f32 v27, v27, v181, v169
	v_mul_f32_e32 v152, v29, v29
	v_mul_f32_e32 v153, v31, v31
	v_mul_f32_e32 v182, v25, v25
	v_mul_f32_e32 v183, v27, v27
	v_fmac_f32_e32 v152, v28, v28
	v_fmac_f32_e32 v153, v30, v30
	v_fmac_f32_e32 v182, v24, v24
	v_fmac_f32_e32 v183, v26, v26
	v_add_f32_e32 v152, v152, v153
	v_add_f32_e32 v182, v182, v183
	v_add_f32_e32 v224, v152, v182
	s_waitcnt lgkmcnt(0)
	v_add_f32_e32 v251, v251, v252
	ds_bpermute_b32 v252, v150, v251
	v_lshlrev_b32_e32 v162, 16, v226
	v_and_b32_e32 v163, 0xffff0000, v226
	v_lshlrev_b32_e32 v170, 16, v230
	v_and_b32_e32 v171, 0xffff0000, v230
	v_lshlrev_b32_e32 v164, 16, v227
	v_and_b32_e32 v165, 0xffff0000, v227
	v_lshlrev_b32_e32 v172, 16, v231
	v_and_b32_e32 v173, 0xffff0000, v231
	v_lshlrev_b32_e32 v166, 16, v228
	v_and_b32_e32 v167, 0xffff0000, v228
	v_lshlrev_b32_e32 v174, 16, v232
	v_and_b32_e32 v175, 0xffff0000, v232
	v_lshlrev_b32_e32 v168, 16, v229
	v_and_b32_e32 v169, 0xffff0000, v229
	v_lshlrev_b32_e32 v180, 16, v233
	v_and_b32_e32 v181, 0xffff0000, v233
	v_mul_f32_e32 v20, v20, v151
	v_mul_f32_e32 v21, v21, v151
	v_mul_f32_e32 v22, v22, v151
	v_mul_f32_e32 v23, v23, v151
	v_mul_f32_e32 v16, v16, v151
	v_mul_f32_e32 v17, v17, v151
	v_mul_f32_e32 v18, v18, v151
	v_mul_f32_e32 v19, v19, v151
	v_mul_f32_e32 v20, 0xbfb8aa3b, v20
	v_mul_f32_e32 v21, 0xbfb8aa3b, v21
	v_mul_f32_e32 v22, 0xbfb8aa3b, v22
	v_mul_f32_e32 v23, 0xbfb8aa3b, v23
	v_mul_f32_e32 v16, 0xbfb8aa3b, v16
	v_mul_f32_e32 v17, 0xbfb8aa3b, v17
	v_mul_f32_e32 v18, 0xbfb8aa3b, v18
	v_mul_f32_e32 v19, 0xbfb8aa3b, v19
	v_exp_f32_e32 v20, v20
	v_exp_f32_e32 v21, v21
	v_exp_f32_e32 v22, v22
	v_exp_f32_e32 v23, v23
	v_exp_f32_e32 v16, v16
	v_exp_f32_e32 v17, v17
	v_exp_f32_e32 v18, v18
	v_exp_f32_e32 v19, v19
	v_add_f32_e32 v20, 1.0, v20
	v_add_f32_e32 v21, 1.0, v21
	v_add_f32_e32 v22, 1.0, v22
	v_add_f32_e32 v23, 1.0, v23
	v_add_f32_e32 v16, 1.0, v16
	v_add_f32_e32 v17, 1.0, v17
	v_add_f32_e32 v18, 1.0, v18
	v_add_f32_e32 v19, 1.0, v19
	v_rcp_f32_e32 v20, v20
	v_rcp_f32_e32 v21, v21
	v_rcp_f32_e32 v22, v22
	v_rcp_f32_e32 v23, v23
	v_rcp_f32_e32 v16, v16
	v_rcp_f32_e32 v17, v17
	v_rcp_f32_e32 v18, v18
	v_rcp_f32_e32 v19, v19
	v_fma_f32 v20, v20, v170, v162
	v_fma_f32 v21, v21, v171, v163
	v_fma_f32 v22, v22, v172, v164
	v_fma_f32 v23, v23, v173, v165
	v_fma_f32 v16, v16, v174, v166
	v_fma_f32 v17, v17, v175, v167
	v_fma_f32 v18, v18, v180, v168
	v_fma_f32 v19, v19, v181, v169
	v_mul_f32_e32 v152, v21, v21
	v_mul_f32_e32 v153, v23, v23
	v_mul_f32_e32 v182, v17, v17
	v_mul_f32_e32 v183, v19, v19
	v_fmac_f32_e32 v152, v20, v20
	v_fmac_f32_e32 v153, v22, v22
	v_fmac_f32_e32 v182, v16, v16
	v_fmac_f32_e32 v183, v18, v18
	v_add_f32_e32 v152, v152, v153
	v_add_f32_e32 v182, v182, v183
	v_add_f32_e32 v250, v152, v182
	s_waitcnt lgkmcnt(0)
	v_add_f32_e32 v253, v251, v252
	s_and_saveexec_b64 s[44:45], s[6:7]
	global_atomic_add_f32 v148, v253, s[16:17] offset:576
	s_or_b64 exec, exec, s[44:45]
	v_add_f32_e32 v251, v224, v250
	ds_bpermute_b32 v252, v149, v251
	s_waitcnt vmcnt(3)
	v_fmamk_f32 v151, v179, 0x3a000000, v160
	v_mul_f32_e32 v152, 0x4b800000, v151
	v_cmp_gt_f32_e32 vcc, s65, v151
	s_nop 1
	v_cndmask_b32_e32 v151, v151, v152, vcc
	v_rsq_f32_e32 v151, v151
	s_nop 0
	v_mul_f32_e32 v152, 0x45800000, v151
	v_cndmask_b32_e32 v151, v151, v152, vcc
	v_lshlrev_b32_e32 v162, 16, v234
	v_and_b32_e32 v163, 0xffff0000, v234
	v_lshlrev_b32_e32 v170, 16, v238
	v_and_b32_e32 v171, 0xffff0000, v238
	v_lshlrev_b32_e32 v164, 16, v235
	v_and_b32_e32 v165, 0xffff0000, v235
	v_lshlrev_b32_e32 v172, 16, v239
	v_and_b32_e32 v173, 0xffff0000, v239
	v_lshlrev_b32_e32 v166, 16, v236
	v_and_b32_e32 v167, 0xffff0000, v236
	v_lshlrev_b32_e32 v174, 16, v240
	v_and_b32_e32 v175, 0xffff0000, v240
	v_lshlrev_b32_e32 v168, 16, v237
	v_and_b32_e32 v169, 0xffff0000, v237
	v_lshlrev_b32_e32 v180, 16, v241
	v_and_b32_e32 v181, 0xffff0000, v241
	v_mul_f32_e32 v12, v12, v151
	v_mul_f32_e32 v13, v13, v151
	v_mul_f32_e32 v14, v14, v151
	v_mul_f32_e32 v15, v15, v151
	v_mul_f32_e32 v8, v8, v151
	v_mul_f32_e32 v9, v9, v151
	v_mul_f32_e32 v10, v10, v151
	v_mul_f32_e32 v11, v11, v151
	v_mul_f32_e32 v12, 0xbfb8aa3b, v12
	v_mul_f32_e32 v13, 0xbfb8aa3b, v13
	v_mul_f32_e32 v14, 0xbfb8aa3b, v14
	v_mul_f32_e32 v15, 0xbfb8aa3b, v15
	v_mul_f32_e32 v8, 0xbfb8aa3b, v8
	v_mul_f32_e32 v9, 0xbfb8aa3b, v9
	v_mul_f32_e32 v10, 0xbfb8aa3b, v10
	v_mul_f32_e32 v11, 0xbfb8aa3b, v11
	v_exp_f32_e32 v12, v12
	v_exp_f32_e32 v13, v13
	v_exp_f32_e32 v14, v14
	v_exp_f32_e32 v15, v15
	v_exp_f32_e32 v8, v8
	v_exp_f32_e32 v9, v9
	v_exp_f32_e32 v10, v10
	v_exp_f32_e32 v11, v11
	v_add_f32_e32 v12, 1.0, v12
	v_add_f32_e32 v13, 1.0, v13
	v_add_f32_e32 v14, 1.0, v14
	v_add_f32_e32 v15, 1.0, v15
	v_add_f32_e32 v8, 1.0, v8
	v_add_f32_e32 v9, 1.0, v9
	v_add_f32_e32 v10, 1.0, v10
	v_add_f32_e32 v11, 1.0, v11
	v_rcp_f32_e32 v12, v12
	v_rcp_f32_e32 v13, v13
	v_rcp_f32_e32 v14, v14
	v_rcp_f32_e32 v15, v15
	v_rcp_f32_e32 v8, v8
	v_rcp_f32_e32 v9, v9
	v_rcp_f32_e32 v10, v10
	v_rcp_f32_e32 v11, v11
	v_fma_f32 v12, v12, v170, v162
	v_fma_f32 v13, v13, v171, v163
	v_fma_f32 v14, v14, v172, v164
	v_fma_f32 v15, v15, v173, v165
	v_fma_f32 v8, v8, v174, v166
	v_fma_f32 v9, v9, v175, v167
	v_fma_f32 v10, v10, v180, v168
	v_fma_f32 v11, v11, v181, v169
	v_mul_f32_e32 v152, v13, v13
	v_mul_f32_e32 v153, v15, v15
	v_mul_f32_e32 v182, v9, v9
	v_mul_f32_e32 v183, v11, v11
	v_fmac_f32_e32 v152, v12, v12
	v_fmac_f32_e32 v153, v14, v14
	v_fmac_f32_e32 v182, v8, v8
	v_fmac_f32_e32 v183, v10, v10
	v_add_f32_e32 v152, v152, v153
	v_add_f32_e32 v182, v182, v183
	v_add_f32_e32 v224, v152, v182
	s_waitcnt lgkmcnt(0)
	v_add_f32_e32 v251, v251, v252
	ds_bpermute_b32 v252, v150, v251
	v_lshlrev_b32_e32 v162, 16, v242
	v_and_b32_e32 v163, 0xffff0000, v242
	v_lshlrev_b32_e32 v170, 16, v246
	v_and_b32_e32 v171, 0xffff0000, v246
	v_lshlrev_b32_e32 v164, 16, v243
	v_and_b32_e32 v165, 0xffff0000, v243
	v_lshlrev_b32_e32 v172, 16, v247
	v_and_b32_e32 v173, 0xffff0000, v247
	v_lshlrev_b32_e32 v166, 16, v244
	v_and_b32_e32 v167, 0xffff0000, v244
	v_lshlrev_b32_e32 v174, 16, v248
	v_and_b32_e32 v175, 0xffff0000, v248
	v_lshlrev_b32_e32 v168, 16, v245
	v_and_b32_e32 v169, 0xffff0000, v245
	v_lshlrev_b32_e32 v180, 16, v249
	v_and_b32_e32 v181, 0xffff0000, v249
	v_mul_f32_e32 v4, v4, v151
	v_mul_f32_e32 v5, v5, v151
	v_mul_f32_e32 v6, v6, v151
	v_mul_f32_e32 v7, v7, v151
	v_mul_f32_e32 v0, v0, v151
	v_mul_f32_e32 v1, v1, v151
	v_mul_f32_e32 v2, v2, v151
	v_mul_f32_e32 v3, v3, v151
	v_mul_f32_e32 v4, 0xbfb8aa3b, v4
	v_mul_f32_e32 v5, 0xbfb8aa3b, v5
	v_mul_f32_e32 v6, 0xbfb8aa3b, v6
	v_mul_f32_e32 v7, 0xbfb8aa3b, v7
	v_mul_f32_e32 v0, 0xbfb8aa3b, v0
	v_mul_f32_e32 v1, 0xbfb8aa3b, v1
	v_mul_f32_e32 v2, 0xbfb8aa3b, v2
	v_mul_f32_e32 v3, 0xbfb8aa3b, v3
	v_exp_f32_e32 v4, v4
	v_exp_f32_e32 v5, v5
	v_exp_f32_e32 v6, v6
	v_exp_f32_e32 v7, v7
	v_exp_f32_e32 v0, v0
	v_exp_f32_e32 v1, v1
	v_exp_f32_e32 v2, v2
	v_exp_f32_e32 v3, v3
	v_add_f32_e32 v4, 1.0, v4
	v_add_f32_e32 v5, 1.0, v5
	v_add_f32_e32 v6, 1.0, v6
	v_add_f32_e32 v7, 1.0, v7
	v_add_f32_e32 v0, 1.0, v0
	v_add_f32_e32 v1, 1.0, v1
	v_add_f32_e32 v2, 1.0, v2
	v_add_f32_e32 v3, 1.0, v3
	v_rcp_f32_e32 v4, v4
	v_rcp_f32_e32 v5, v5
	v_rcp_f32_e32 v6, v6
	v_rcp_f32_e32 v7, v7
	v_rcp_f32_e32 v0, v0
	v_rcp_f32_e32 v1, v1
	v_rcp_f32_e32 v2, v2
	v_rcp_f32_e32 v3, v3
	v_fma_f32 v4, v4, v170, v162
	v_fma_f32 v5, v5, v171, v163
	v_fma_f32 v6, v6, v172, v164
	v_fma_f32 v7, v7, v173, v165
	v_fma_f32 v0, v0, v174, v166
	v_fma_f32 v1, v1, v175, v167
	v_fma_f32 v2, v2, v180, v168
	v_fma_f32 v3, v3, v181, v169
	v_mul_f32_e32 v152, v5, v5
	v_mul_f32_e32 v153, v7, v7
	v_mul_f32_e32 v182, v1, v1
	v_mul_f32_e32 v183, v3, v3
	v_fmac_f32_e32 v152, v4, v4
	v_fmac_f32_e32 v153, v6, v6
	v_fmac_f32_e32 v182, v0, v0
	v_fmac_f32_e32 v183, v2, v2
	v_add_f32_e32 v152, v152, v153
	v_add_f32_e32 v182, v182, v183
	v_add_f32_e32 v250, v152, v182
	s_waitcnt lgkmcnt(0)
	v_add_f32_e32 v253, v251, v252
	s_and_saveexec_b64 s[44:45], s[6:7]
	global_atomic_add_f32 v148, v253, s[16:17] offset:640
	s_or_b64 exec, exec, s[44:45]
	v_add_f32_e32 v251, v224, v250
	ds_bpermute_b32 v252, v149, v251
	s_waitcnt lgkmcnt(0)
	v_add_f32_e32 v251, v251, v252
	ds_bpermute_b32 v252, v150, v251
	s_waitcnt lgkmcnt(0)
	v_add_f32_e32 v253, v251, v252
	s_and_saveexec_b64 s[44:45], s[6:7]
	global_atomic_add_f32 v148, v253, s[16:17] offset:704
	s_or_b64 exec, exec, s[44:45]
	v_lshlrev_b32_e32 v152, 2, v144
	global_load_dwordx4 v[200:203], v152, s[18:19] offset:0
	global_load_dwordx4 v[204:207], v152, s[18:19] offset:16
	global_load_dwordx4 v[208:211], v152, s[18:19] offset:512
	global_load_dwordx4 v[212:215], v152, s[18:19] offset:528
	s_waitcnt vmcnt(0)
	s_barrier
	s_add_i32 s99, s99, 1
	s_lshl_b32 s86, s99, 3
	v_readfirstlane_b32 s87, v225
	s_nop 3
	s_cmp_lt_u32 s87, 64
	s_cbranch_scc0 .Lp4_gs_join
	s_mov_b64 s[92:93], exec
	s_mov_b64 exec, 1
	v_mov_b32_e32 v192, 0
	v_mov_b32_e32 v193, 1
	global_atomic_add v192, v193, s[88:89]
	s_mov_b32 s90, 0
.Lp4_gs_poll:
	global_load_dword v194, v192, s[88:89] sc1
	s_waitcnt vmcnt(0)
	v_readfirstlane_b32 s87, v194
	s_nop 3
	s_cmp_ge_u32 s87, s86
	s_cbranch_scc1 .Lp4_gs_done
	s_sleep 1
	s_add_i32 s90, s90, 1
	s_cmp_lt_u32 s90, 0x8000
	s_cbranch_scc1 .Lp4_gs_poll
.Lp4_gs_done:
	s_mov_b64 exec, s[92:93]
.Lp4_gs_join:
	s_barrier
	global_load_dword v184, v148, s[16:17] offset:0 sc1
	global_load_dword v185, v148, s[16:17] offset:64 sc1
	global_load_dword v186, v148, s[16:17] offset:128 sc1
	global_load_dword v187, v148, s[16:17] offset:192 sc1
	global_load_dword v188, v148, s[16:17] offset:512 sc1
	global_load_dword v189, v148, s[16:17] offset:576 sc1
	global_load_dword v190, v148, s[16:17] offset:640 sc1
	global_load_dword v191, v148, s[16:17] offset:704 sc1
	v_lshlrev_b32_e32 v147, 2, v145
	s_waitcnt vmcnt(7)
	v_fmamk_f32 v151, v184, 0x3a000000, v160
	v_mul_f32_e32 v152, 0x4b800000, v151
	v_cmp_gt_f32_e32 vcc, s65, v151
	s_nop 1
	v_cndmask_b32_e32 v151, v151, v152, vcc
	v_rsq_f32_e32 v151, v151
	s_nop 0
	v_mul_f32_e32 v152, 0x45800000, v151
	v_cndmask_b32_e32 v151, v151, v152, vcc
	s_mov_b64 s[52:53], s[20:21]
	v_mul_f32_e32 v124, v151, v124
	v_mul_f32_e32 v125, v151, v125
	v_mul_f32_e32 v126, v151, v126
	v_mul_f32_e32 v127, v151, v127
	v_mul_f32_e32 v120, v151, v120
	v_mul_f32_e32 v121, v151, v121
	v_mul_f32_e32 v122, v151, v122
	v_mul_f32_e32 v123, v151, v123
	v_mul_f32_e32 v124, v200, v124
	v_mul_f32_e32 v125, v201, v125
	v_mul_f32_e32 v126, v202, v126
	v_mul_f32_e32 v127, v203, v127
	v_mul_f32_e32 v120, v204, v120
	v_mul_f32_e32 v121, v205, v121
	v_mul_f32_e32 v122, v206, v122
	v_mul_f32_e32 v123, v207, v123
	global_store_dwordx4 v147, v[124:127], s[52:53] offset:0
	global_store_dwordx4 v147, v[120:123], s[52:53] offset:16
	v_mul_f32_e32 v116, v151, v116
	v_mul_f32_e32 v117, v151, v117
	v_mul_f32_e32 v118, v151, v118
	v_mul_f32_e32 v119, v151, v119
	v_mul_f32_e32 v112, v151, v112
	v_mul_f32_e32 v113, v151, v113
	v_mul_f32_e32 v114, v151, v114
	v_mul_f32_e32 v115, v151, v115
	v_mul_f32_e32 v116, v208, v116
	v_mul_f32_e32 v117, v209, v117
	v_mul_f32_e32 v118, v210, v118
	v_mul_f32_e32 v119, v211, v119
	v_mul_f32_e32 v112, v212, v112
	v_mul_f32_e32 v113, v213, v113
	v_mul_f32_e32 v114, v214, v114
	v_mul_f32_e32 v115, v215, v115
	global_store_dwordx4 v147, v[116:119], s[52:53] offset:512
	global_store_dwordx4 v147, v[112:115], s[52:53] offset:528
	s_waitcnt vmcnt(10)
	v_fmamk_f32 v151, v185, 0x3a000000, v160
	v_mul_f32_e32 v152, 0x4b800000, v151
	v_cmp_gt_f32_e32 vcc, s65, v151
	s_nop 1
	v_cndmask_b32_e32 v151, v151, v152, vcc
	v_rsq_f32_e32 v151, v151
	s_nop 0
	v_mul_f32_e32 v152, 0x45800000, v151
	v_cndmask_b32_e32 v151, v151, v152, vcc
	s_add_u32 s52, s20, 0x20000
	s_addc_u32 s53, s21, 0
	v_mul_f32_e32 v108, v151, v108
	v_mul_f32_e32 v109, v151, v109
	v_mul_f32_e32 v110, v151, v110
	v_mul_f32_e32 v111, v151, v111
	v_mul_f32_e32 v104, v151, v104
	v_mul_f32_e32 v105, v151, v105
	v_mul_f32_e32 v106, v151, v106
	v_mul_f32_e32 v107, v151, v107
	v_mul_f32_e32 v108, v200, v108
	v_mul_f32_e32 v109, v201, v109
	v_mul_f32_e32 v110, v202, v110
	v_mul_f32_e32 v111, v203, v111
	v_mul_f32_e32 v104, v204, v104
	v_mul_f32_e32 v105, v205, v105
	v_mul_f32_e32 v106, v206, v106
	v_mul_f32_e32 v107, v207, v107
	global_store_dwordx4 v147, v[108:111], s[52:53] offset:0
	global_store_dwordx4 v147, v[104:107], s[52:53] offset:16
	v_mul_f32_e32 v100, v151, v100
	v_mul_f32_e32 v101, v151, v101
	v_mul_f32_e32 v102, v151, v102
	v_mul_f32_e32 v103, v151, v103
	v_mul_f32_e32 v96, v151, v96
	v_mul_f32_e32 v97, v151, v97
	v_mul_f32_e32 v98, v151, v98
	v_mul_f32_e32 v99, v151, v99
	v_mul_f32_e32 v100, v208, v100
	v_mul_f32_e32 v101, v209, v101
	v_mul_f32_e32 v102, v210, v102
	v_mul_f32_e32 v103, v211, v103
	v_mul_f32_e32 v96, v212, v96
	v_mul_f32_e32 v97, v213, v97
	v_mul_f32_e32 v98, v214, v98
	v_mul_f32_e32 v99, v215, v99
	global_store_dwordx4 v147, v[100:103], s[52:53] offset:512
	global_store_dwordx4 v147, v[96:99], s[52:53] offset:528
	s_waitcnt vmcnt(13)
	v_fmamk_f32 v151, v186, 0x3a000000, v160
	v_mul_f32_e32 v152, 0x4b800000, v151
	v_cmp_gt_f32_e32 vcc, s65, v151
	s_nop 1
	v_cndmask_b32_e32 v151, v151, v152, vcc
	v_rsq_f32_e32 v151, v151
	s_nop 0
	v_mul_f32_e32 v152, 0x45800000, v151
	v_cndmask_b32_e32 v151, v151, v152, vcc
	s_add_u32 s52, s20, 0x40000
	s_addc_u32 s53, s21, 0
	v_mul_f32_e32 v92, v151, v92
	v_mul_f32_e32 v93, v151, v93
	v_mul_f32_e32 v94, v151, v94
	v_mul_f32_e32 v95, v151, v95
	v_mul_f32_e32 v88, v151, v88
	v_mul_f32_e32 v89, v151, v89
	v_mul_f32_e32 v90, v151, v90
	v_mul_f32_e32 v91, v151, v91
	v_mul_f32_e32 v92, v200, v92
	v_mul_f32_e32 v93, v201, v93
	v_mul_f32_e32 v94, v202, v94
	v_mul_f32_e32 v95, v203, v95
	v_mul_f32_e32 v88, v204, v88
	v_mul_f32_e32 v89, v205, v89
	v_mul_f32_e32 v90, v206, v90
	v_mul_f32_e32 v91, v207, v91
	global_store_dwordx4 v147, v[92:95], s[52:53] offset:0
	global_store_dwordx4 v147, v[88:91], s[52:53] offset:16
	v_mul_f32_e32 v84, v151, v84
	v_mul_f32_e32 v85, v151, v85
	v_mul_f32_e32 v86, v151, v86
	v_mul_f32_e32 v87, v151, v87
	v_mul_f32_e32 v80, v151, v80
	v_mul_f32_e32 v81, v151, v81
	v_mul_f32_e32 v82, v151, v82
	v_mul_f32_e32 v83, v151, v83
	v_mul_f32_e32 v84, v208, v84
	v_mul_f32_e32 v85, v209, v85
	v_mul_f32_e32 v86, v210, v86
	v_mul_f32_e32 v87, v211, v87
	v_mul_f32_e32 v80, v212, v80
	v_mul_f32_e32 v81, v213, v81
	v_mul_f32_e32 v82, v214, v82
	v_mul_f32_e32 v83, v215, v83
	global_store_dwordx4 v147, v[84:87], s[52:53] offset:512
	global_store_dwordx4 v147, v[80:83], s[52:53] offset:528
	s_waitcnt vmcnt(16)
	v_fmamk_f32 v151, v187, 0x3a000000, v160
	v_mul_f32_e32 v152, 0x4b800000, v151
	v_cmp_gt_f32_e32 vcc, s65, v151
	s_nop 1
	v_cndmask_b32_e32 v151, v151, v152, vcc
	v_rsq_f32_e32 v151, v151
	s_nop 0
	v_mul_f32_e32 v152, 0x45800000, v151
	v_cndmask_b32_e32 v151, v151, v152, vcc
	s_add_u32 s52, s20, 0x60000
	s_addc_u32 s53, s21, 0
	v_mul_f32_e32 v76, v151, v76
	v_mul_f32_e32 v77, v151, v77
	v_mul_f32_e32 v78, v151, v78
	v_mul_f32_e32 v79, v151, v79
	v_mul_f32_e32 v72, v151, v72
	v_mul_f32_e32 v73, v151, v73
	v_mul_f32_e32 v74, v151, v74
	v_mul_f32_e32 v75, v151, v75
	v_mul_f32_e32 v76, v200, v76
	v_mul_f32_e32 v77, v201, v77
	v_mul_f32_e32 v78, v202, v78
	v_mul_f32_e32 v79, v203, v79
	v_mul_f32_e32 v72, v204, v72
	v_mul_f32_e32 v73, v205, v73
	v_mul_f32_e32 v74, v206, v74
	v_mul_f32_e32 v75, v207, v75
	global_store_dwordx4 v147, v[76:79], s[52:53] offset:0
	global_store_dwordx4 v147, v[72:75], s[52:53] offset:16
	v_mul_f32_e32 v68, v151, v68
	v_mul_f32_e32 v69, v151, v69
	v_mul_f32_e32 v70, v151, v70
	v_mul_f32_e32 v71, v151, v71
	v_mul_f32_e32 v64, v151, v64
	v_mul_f32_e32 v65, v151, v65
	v_mul_f32_e32 v66, v151, v66
	v_mul_f32_e32 v67, v151, v67
	v_mul_f32_e32 v68, v208, v68
	v_mul_f32_e32 v69, v209, v69
	v_mul_f32_e32 v70, v210, v70
	v_mul_f32_e32 v71, v211, v71
	v_mul_f32_e32 v64, v212, v64
	v_mul_f32_e32 v65, v213, v65
	v_mul_f32_e32 v66, v214, v66
	v_mul_f32_e32 v67, v215, v67
	global_store_dwordx4 v147, v[68:71], s[52:53] offset:512
	global_store_dwordx4 v147, v[64:67], s[52:53] offset:528
	s_waitcnt vmcnt(19)
	v_fmamk_f32 v151, v188, 0x3a000000, v160
	v_mul_f32_e32 v152, 0x4b800000, v151
	v_cmp_gt_f32_e32 vcc, s65, v151
	s_nop 1
	v_cndmask_b32_e32 v151, v151, v152, vcc
	v_rsq_f32_e32 v151, v151
	s_nop 0
	v_mul_f32_e32 v152, 0x45800000, v151
	v_cndmask_b32_e32 v151, v151, v152, vcc
	s_add_u32 s52, s20, 0x100000
	s_addc_u32 s53, s21, 0
	v_mul_f32_e32 v60, v151, v60
	v_mul_f32_e32 v61, v151, v61
	v_mul_f32_e32 v62, v151, v62
	v_mul_f32_e32 v63, v151, v63
	v_mul_f32_e32 v56, v151, v56
	v_mul_f32_e32 v57, v151, v57
	v_mul_f32_e32 v58, v151, v58
	v_mul_f32_e32 v59, v151, v59
	v_mul_f32_e32 v60, v200, v60
	v_mul_f32_e32 v61, v201, v61
	v_mul_f32_e32 v62, v202, v62
	v_mul_f32_e32 v63, v203, v63
	v_mul_f32_e32 v56, v204, v56
	v_mul_f32_e32 v57, v205, v57
	v_mul_f32_e32 v58, v206, v58
	v_mul_f32_e32 v59, v207, v59
	global_store_dwordx4 v147, v[60:63], s[52:53] offset:0
	global_store_dwordx4 v147, v[56:59], s[52:53] offset:16
	v_mul_f32_e32 v52, v151, v52
	v_mul_f32_e32 v53, v151, v53
	v_mul_f32_e32 v54, v151, v54
	v_mul_f32_e32 v55, v151, v55
	v_mul_f32_e32 v48, v151, v48
	v_mul_f32_e32 v49, v151, v49
	v_mul_f32_e32 v50, v151, v50
	v_mul_f32_e32 v51, v151, v51
	v_mul_f32_e32 v52, v208, v52
	v_mul_f32_e32 v53, v209, v53
	v_mul_f32_e32 v54, v210, v54
	v_mul_f32_e32 v55, v211, v55
	v_mul_f32_e32 v48, v212, v48
	v_mul_f32_e32 v49, v213, v49
	v_mul_f32_e32 v50, v214, v50
	v_mul_f32_e32 v51, v215, v51
	global_store_dwordx4 v147, v[52:55], s[52:53] offset:512
	global_store_dwordx4 v147, v[48:51], s[52:53] offset:528
	s_waitcnt vmcnt(22)
	v_fmamk_f32 v151, v189, 0x3a000000, v160
	v_mul_f32_e32 v152, 0x4b800000, v151
	v_cmp_gt_f32_e32 vcc, s65, v151
	s_nop 1
	v_cndmask_b32_e32 v151, v151, v152, vcc
	v_rsq_f32_e32 v151, v151
	s_nop 0
	v_mul_f32_e32 v152, 0x45800000, v151
	v_cndmask_b32_e32 v151, v151, v152, vcc
	s_add_u32 s52, s20, 0x120000
	s_addc_u32 s53, s21, 0
	v_mul_f32_e32 v44, v151, v44
	v_mul_f32_e32 v45, v151, v45
	v_mul_f32_e32 v46, v151, v46
	v_mul_f32_e32 v47, v151, v47
	v_mul_f32_e32 v40, v151, v40
	v_mul_f32_e32 v41, v151, v41
	v_mul_f32_e32 v42, v151, v42
	v_mul_f32_e32 v43, v151, v43
	v_mul_f32_e32 v44, v200, v44
	v_mul_f32_e32 v45, v201, v45
	v_mul_f32_e32 v46, v202, v46
	v_mul_f32_e32 v47, v203, v47
	v_mul_f32_e32 v40, v204, v40
	v_mul_f32_e32 v41, v205, v41
	v_mul_f32_e32 v42, v206, v42
	v_mul_f32_e32 v43, v207, v43
	global_store_dwordx4 v147, v[44:47], s[52:53] offset:0
	global_store_dwordx4 v147, v[40:43], s[52:53] offset:16
	v_mul_f32_e32 v36, v151, v36
	v_mul_f32_e32 v37, v151, v37
	v_mul_f32_e32 v38, v151, v38
	v_mul_f32_e32 v39, v151, v39
	v_mul_f32_e32 v32, v151, v32
	v_mul_f32_e32 v33, v151, v33
	v_mul_f32_e32 v34, v151, v34
	v_mul_f32_e32 v35, v151, v35
	v_mul_f32_e32 v36, v208, v36
	v_mul_f32_e32 v37, v209, v37
	v_mul_f32_e32 v38, v210, v38
	v_mul_f32_e32 v39, v211, v39
	v_mul_f32_e32 v32, v212, v32
	v_mul_f32_e32 v33, v213, v33
	v_mul_f32_e32 v34, v214, v34
	v_mul_f32_e32 v35, v215, v35
	global_store_dwordx4 v147, v[36:39], s[52:53] offset:512
	global_store_dwordx4 v147, v[32:35], s[52:53] offset:528
	s_waitcnt vmcnt(25)
	v_fmamk_f32 v151, v190, 0x3a000000, v160
	v_mul_f32_e32 v152, 0x4b800000, v151
	v_cmp_gt_f32_e32 vcc, s65, v151
	s_nop 1
	v_cndmask_b32_e32 v151, v151, v152, vcc
	v_rsq_f32_e32 v151, v151
	s_nop 0
	v_mul_f32_e32 v152, 0x45800000, v151
	v_cndmask_b32_e32 v151, v151, v152, vcc
	s_add_u32 s52, s20, 0x140000
	s_addc_u32 s53, s21, 0
	v_mul_f32_e32 v28, v151, v28
	v_mul_f32_e32 v29, v151, v29
	v_mul_f32_e32 v30, v151, v30
	v_mul_f32_e32 v31, v151, v31
	v_mul_f32_e32 v24, v151, v24
	v_mul_f32_e32 v25, v151, v25
	v_mul_f32_e32 v26, v151, v26
	v_mul_f32_e32 v27, v151, v27
	v_mul_f32_e32 v28, v200, v28
	v_mul_f32_e32 v29, v201, v29
	v_mul_f32_e32 v30, v202, v30
	v_mul_f32_e32 v31, v203, v31
	v_mul_f32_e32 v24, v204, v24
	v_mul_f32_e32 v25, v205, v25
	v_mul_f32_e32 v26, v206, v26
	v_mul_f32_e32 v27, v207, v27
	global_store_dwordx4 v147, v[28:31], s[52:53] offset:0
	global_store_dwordx4 v147, v[24:27], s[52:53] offset:16
	v_mul_f32_e32 v20, v151, v20
	v_mul_f32_e32 v21, v151, v21
	v_mul_f32_e32 v22, v151, v22
	v_mul_f32_e32 v23, v151, v23
	v_mul_f32_e32 v16, v151, v16
	v_mul_f32_e32 v17, v151, v17
	v_mul_f32_e32 v18, v151, v18
	v_mul_f32_e32 v19, v151, v19
	v_mul_f32_e32 v20, v208, v20
	v_mul_f32_e32 v21, v209, v21
	v_mul_f32_e32 v22, v210, v22
	v_mul_f32_e32 v23, v211, v23
	v_mul_f32_e32 v16, v212, v16
	v_mul_f32_e32 v17, v213, v17
	v_mul_f32_e32 v18, v214, v18
	v_mul_f32_e32 v19, v215, v19
	global_store_dwordx4 v147, v[20:23], s[52:53] offset:512
	global_store_dwordx4 v147, v[16:19], s[52:53] offset:528
	s_waitcnt vmcnt(28)
	v_fmamk_f32 v151, v191, 0x3a000000, v160
	v_mul_f32_e32 v152, 0x4b800000, v151
	v_cmp_gt_f32_e32 vcc, s65, v151
	s_nop 1
	v_cndmask_b32_e32 v151, v151, v152, vcc
	v_rsq_f32_e32 v151, v151
	s_nop 0
	v_mul_f32_e32 v152, 0x45800000, v151
	v_cndmask_b32_e32 v151, v151, v152, vcc
	s_add_u32 s52, s20, 0x160000
	s_addc_u32 s53, s21, 0
	v_mul_f32_e32 v12, v151, v12
	v_mul_f32_e32 v13, v151, v13
	v_mul_f32_e32 v14, v151, v14
	v_mul_f32_e32 v15, v151, v15
	v_mul_f32_e32 v8, v151, v8
	v_mul_f32_e32 v9, v151, v9
	v_mul_f32_e32 v10, v151, v10
	v_mul_f32_e32 v11, v151, v11
	v_mul_f32_e32 v12, v200, v12
	v_mul_f32_e32 v13, v201, v13
	v_mul_f32_e32 v14, v202, v14
	v_mul_f32_e32 v15, v203, v15
	v_mul_f32_e32 v8, v204, v8
	v_mul_f32_e32 v9, v205, v9
	v_mul_f32_e32 v10, v206, v10
	v_mul_f32_e32 v11, v207, v11
	global_store_dwordx4 v147, v[12:15], s[52:53] offset:0
	global_store_dwordx4 v147, v[8:11], s[52:53] offset:16
	v_mul_f32_e32 v4, v151, v4
	v_mul_f32_e32 v5, v151, v5
	v_mul_f32_e32 v6, v151, v6
	v_mul_f32_e32 v7, v151, v7
	v_mul_f32_e32 v0, v151, v0
	v_mul_f32_e32 v1, v151, v1
	v_mul_f32_e32 v2, v151, v2
	v_mul_f32_e32 v3, v151, v3
	v_mul_f32_e32 v4, v208, v4
	v_mul_f32_e32 v5, v209, v5
	v_mul_f32_e32 v6, v210, v6
	v_mul_f32_e32 v7, v211, v7
	v_mul_f32_e32 v0, v212, v0
	v_mul_f32_e32 v1, v213, v1
	v_mul_f32_e32 v2, v214, v2
	v_mul_f32_e32 v3, v215, v3
	global_store_dwordx4 v147, v[4:7], s[52:53] offset:512
	global_store_dwordx4 v147, v[0:3], s[52:53] offset:528
	s_andn2_b64 vcc, exec, s[4:5]
	s_mov_b64 s[4:5], -1
	s_cbranch_vccnz .LBB0_780
	s_andn2_b64 vcc, exec, s[8:9]
	s_cbranch_vccnz .LBB0_779
	s_barrier
	s_branch .LBB0_779

.LBB0_811:
	s_endpgm
	s_waitcnt vmcnt(0)
	s_waitcnt lgkmcnt(0)
	s_barrier
	s_and_saveexec_b64 s[2:3], s[0:1]
	s_cbranch_execz .LBB0_863
	s_add_i32 s0, 0, 0x20000
	v_mov_b32_e32 v0, s0
	s_waitcnt vmcnt(0) expcnt(0) lgkmcnt(0)
	ds_read_b32 v2, v0
	s_add_i32 s0, 0, 0x20004
	v_mov_b32_e32 v0, s0
	ds_read_b32 v0, v0
	s_waitcnt lgkmcnt(1)
	v_cmp_ne_u32_e32 vcc, 0, v2
	s_cbranch_vccnz .LBB0_827
	s_add_u32 s0, s22, 0x80200
	s_addc_u32 s1, s23, 0
	s_add_u32 s4, s22, 0x80400
	s_addc_u32 s5, s23, 0
	s_add_u32 s6, s22, 0x80500
	s_addc_u32 s7, s23, 0
	s_add_u32 s8, s22, 0x80600
	s_addc_u32 s9, s23, 0
	s_add_u32 s12, s22, 0x80700
	s_addc_u32 s13, s23, 0
	s_add_u32 s14, s22, 0x80800
	s_addc_u32 s15, s23, 0
	s_add_u32 s28, s22, 0x80900
	s_addc_u32 s29, s23, 0
	s_add_u32 s30, s22, 0x80a00
	s_addc_u32 s31, s23, 0
	s_add_u32 s34, s22, 0x80b00
	s_addc_u32 s35, s23, 0
	s_add_u32 s36, s22, 0x80c00
	s_addc_u32 s37, s23, 0
	s_add_u32 s38, s22, 0x80d00
	s_addc_u32 s39, s23, 0
	s_add_u32 s40, s22, 0x80e00
	s_addc_u32 s41, s23, 0
	s_add_u32 s42, s22, 0x80f00
	s_addc_u32 s43, s23, 0
	s_add_u32 s44, s22, 0x81000
	s_addc_u32 s45, s23, 0
	s_add_u32 s46, s22, 0x81100
	s_addc_u32 s47, s23, 0
	s_add_u32 s48, s22, 0x81200
	s_addc_u32 s49, s23, 0
	s_mul_i32 s25, s25, s80
	s_add_u32 s50, s22, 0x81300
	s_mul_i32 s25, s25, s24
	s_addc_u32 s51, s23, 0
	s_mov_b32 s58, 1
	v_mov_b32_e32 v16, 0
	s_branch .LBB0_815
